# GEMM k-loops P1/P5/P7: ds_reads issued right after barrier, LDS-DMA issue interleaved into MFMA stream with SGPR m0 arithmetic, counted lgkmcnt ladder
# speedup vs baseline: 1.0182x; 1.0046x over previous
.LBB0_160:
	s_mul_hi_i32 s4, s92, 0x88888889
	s_add_i32 s4, s4, s92
	s_lshr_b32 s5, s4, 31
	s_ashr_i32 s4, s4, 3
	s_add_i32 s4, s4, s5
	s_add_i32 s5, s4, s56
	s_mul_i32 s6, s4, 15
	s_sub_i32 s94, s92, s6
	s_lshl_b32 s6, s5, 8
	v_add_u32_e32 v4, s6, v179
	v_ashrrev_i32_e32 v5, 31, v4
	v_lshlrev_b64 v[4:5], 11, v[4:5]
	v_lshl_add_u64 v[6:7], s[28:29], 0, v[4:5]
	v_readfirstlane_b32 s5, v181
	v_lshl_add_u64 v[6:7], v[6:7], 0, v[138:139]
	s_mov_b32 m0, s5
	s_barrier
	global_load_lds_dwordx4 v[6:7], off
	v_add_u32_e32 v6, s6, v180
	s_lshl_b32 s93, s94, 8
	v_ashrrev_i32_e32 v7, 31, v6
	v_add_u32_e32 v0, s93, v179
	v_lshlrev_b64 v[6:7], 11, v[6:7]
	v_ashrrev_i32_e32 v1, 31, v0
	v_add_u32_e32 v2, s93, v180
	v_lshl_add_u64 v[8:9], s[28:29], 0, v[6:7]
	v_readfirstlane_b32 s5, v199
	v_lshlrev_b64 v[0:1], 11, v[0:1]
	v_ashrrev_i32_e32 v3, 31, v2
	v_lshl_add_u64 v[8:9], v[8:9], 0, v[138:139]
	s_mov_b32 m0, s5
	v_readfirstlane_b32 s5, v200
	v_lshl_add_u64 v[0:1], v[130:131], 0, v[0:1]
	v_lshlrev_b64 v[2:3], 11, v[2:3]
	global_load_lds_dwordx4 v[8:9], off
	s_mov_b32 m0, s5
	v_readfirstlane_b32 s5, v201
	v_lshl_add_u64 v[2:3], v[130:131], 0, v[2:3]
	global_load_lds_dwordx4 v[0:1], off
	s_mov_b32 m0, s5
	v_lshl_add_u64 v[8:9], v[130:131], 0, v[4:5]
	v_readfirstlane_b32 s5, v202
	global_load_lds_dwordx4 v[2:3], off
	v_lshl_add_u64 v[10:11], v[8:9], 0, s[14:15]
	s_mov_b32 m0, s5
	v_readfirstlane_b32 s5, v203
	global_load_lds_dwordx4 v[10:11], off
	v_lshl_add_u64 v[10:11], v[130:131], 0, v[6:7]
	v_lshl_add_u64 v[12:13], v[10:11], 0, s[14:15]
	s_mov_b32 m0, s5
	v_readfirstlane_b32 s5, v204
	global_load_lds_dwordx4 v[12:13], off
	v_lshl_add_u64 v[12:13], v[0:1], 0, 64
	s_mov_b32 m0, s5
	v_readfirstlane_b32 s5, v205
	global_load_lds_dwordx4 v[12:13], off
	v_lshl_add_u64 v[12:13], v[2:3], 0, 64
	s_mov_b32 m0, s5
	v_readfirstlane_b32 s5, v206
	global_load_lds_dwordx4 v[12:13], off
	v_lshl_add_u64 v[8:9], v[8:9], 0, s[16:17]
	s_mov_b32 m0, s5
	v_readfirstlane_b32 s5, v207
	global_load_lds_dwordx4 v[8:9], off
	v_lshl_add_u64 v[8:9], v[10:11], 0, s[16:17]
	s_mov_b32 m0, s5
	v_readfirstlane_b32 s5, v208
	global_load_lds_dwordx4 v[8:9], off
	v_lshl_add_u64 v[0:1], v[0:1], 0, s[18:19]
	s_mov_b32 m0, s5
	v_readfirstlane_b32 s5, v209
	global_load_lds_dwordx4 v[0:1], off
	v_lshl_add_u64 v[0:1], v[2:3], 0, s[18:19]
	s_mov_b32 m0, s5
	s_lshl_b32 s5, s92, 8
	global_load_lds_dwordx4 v[0:1], off
	v_add_u32_e32 v0, s5, v179
	s_mulk_i32 s4, 0xf00
	v_subrev_u32_e32 v0, s4, v0
	v_ashrrev_i32_e32 v1, 31, v0
	v_lshlrev_b64 v[0:1], 11, v[0:1]
	v_lshl_add_u64 v[140:141], v[134:135], 0, v[0:1]
	v_add_u32_e32 v0, s5, v180
	v_subrev_u32_e32 v0, s4, v0
	v_ashrrev_i32_e32 v1, 31, v0
	v_lshlrev_b64 v[0:1], 11, v[0:1]
	v_lshl_add_u64 v[142:143], v[134:135], 0, v[0:1]
	v_lshl_add_u64 v[144:145], v[136:137], 0, v[4:5]
	v_lshl_add_u64 v[146:147], v[136:137], 0, v[6:7]
	s_mov_b64 s[4:5], 0
	s_mov_b32 s7, 0x18000
	v_mov_b32_e32 v0, 0
	v_mov_b32_e32 v1, v129
	v_mov_b32_e32 v2, v129
	v_mov_b32_e32 v3, v129
	v_mov_b32_e32 v4, v129
	v_mov_b32_e32 v5, v129
	v_mov_b32_e32 v6, v129
	v_mov_b32_e32 v7, v129
	v_mov_b32_e32 v8, v129
	v_mov_b32_e32 v9, v129
	v_mov_b32_e32 v10, v129
	v_mov_b32_e32 v11, v129
	v_mov_b32_e32 v12, v129
	v_mov_b32_e32 v13, v129
	v_mov_b32_e32 v14, v129
	v_mov_b32_e32 v15, v129
	v_mov_b32_e32 v16, 0
	v_mov_b32_e32 v17, v129
	v_mov_b32_e32 v18, v129
	v_mov_b32_e32 v19, v129
	v_mov_b32_e32 v20, v129
	v_mov_b32_e32 v21, v129
	v_mov_b32_e32 v22, v129
	v_mov_b32_e32 v23, v129
	v_mov_b32_e32 v24, v129
	v_mov_b32_e32 v25, v129
	v_mov_b32_e32 v26, v129
	v_mov_b32_e32 v27, v129
	v_mov_b32_e32 v28, v129
	v_mov_b32_e32 v29, v129
	v_mov_b32_e32 v30, v129
	v_mov_b32_e32 v31, v129
	v_mov_b32_e32 v64, 0
	v_mov_b32_e32 v65, v129
	v_mov_b32_e32 v66, v129
	v_mov_b32_e32 v67, v129
	v_mov_b32_e32 v68, v129
	v_mov_b32_e32 v69, v129
	v_mov_b32_e32 v70, v129
	v_mov_b32_e32 v71, v129
	v_mov_b32_e32 v72, v129
	v_mov_b32_e32 v73, v129
	v_mov_b32_e32 v74, v129
	v_mov_b32_e32 v75, v129
	v_mov_b32_e32 v76, v129
	v_mov_b32_e32 v77, v129
	v_mov_b32_e32 v78, v129
	v_mov_b32_e32 v79, v129
	v_mov_b32_e32 v80, 0
	v_mov_b32_e32 v81, v129
	v_mov_b32_e32 v82, v129
	v_mov_b32_e32 v83, v129
	v_mov_b32_e32 v84, v129
	v_mov_b32_e32 v85, v129
	v_mov_b32_e32 v86, v129
	v_mov_b32_e32 v87, v129
	v_mov_b32_e32 v88, v129
	v_mov_b32_e32 v89, v129
	v_mov_b32_e32 v90, v129
	v_mov_b32_e32 v91, v129
	v_mov_b32_e32 v92, v129
	v_mov_b32_e32 v93, v129
	v_mov_b32_e32 v94, v129
	v_mov_b32_e32 v95, v129
	v_mov_b32_e32 v32, 0
	v_mov_b32_e32 v33, v129
	v_mov_b32_e32 v34, v129
	v_mov_b32_e32 v35, v129
	v_mov_b32_e32 v36, v129
	v_mov_b32_e32 v37, v129
	v_mov_b32_e32 v38, v129
	v_mov_b32_e32 v39, v129
	v_mov_b32_e32 v40, v129
	v_mov_b32_e32 v41, v129
	v_mov_b32_e32 v42, v129
	v_mov_b32_e32 v43, v129
	v_mov_b32_e32 v44, v129
	v_mov_b32_e32 v45, v129
	v_mov_b32_e32 v46, v129
	v_mov_b32_e32 v47, v129
	v_mov_b32_e32 v48, 0
	v_mov_b32_e32 v49, v129
	v_mov_b32_e32 v50, v129
	v_mov_b32_e32 v51, v129
	v_mov_b32_e32 v52, v129
	v_mov_b32_e32 v53, v129
	v_mov_b32_e32 v54, v129
	v_mov_b32_e32 v55, v129
	v_mov_b32_e32 v56, v129
	v_mov_b32_e32 v57, v129
	v_mov_b32_e32 v58, v129
	v_mov_b32_e32 v59, v129
	v_mov_b32_e32 v60, v129
	v_mov_b32_e32 v61, v129
	v_mov_b32_e32 v62, v129
	v_mov_b32_e32 v63, v129
	v_mov_b32_e32 v96, 0
	v_mov_b32_e32 v97, v129
	v_mov_b32_e32 v98, v129
	v_mov_b32_e32 v99, v129
	v_mov_b32_e32 v100, v129
	v_mov_b32_e32 v101, v129
	v_mov_b32_e32 v102, v129
	v_mov_b32_e32 v103, v129
	v_mov_b32_e32 v104, v129
	v_mov_b32_e32 v105, v129
	v_mov_b32_e32 v106, v129
	v_mov_b32_e32 v107, v129
	v_mov_b32_e32 v108, v129
	v_mov_b32_e32 v109, v129
	v_mov_b32_e32 v110, v129
	v_mov_b32_e32 v111, v129
	v_mov_b32_e32 v112, 0
	v_mov_b32_e32 v113, v129
	v_mov_b32_e32 v114, v129
	v_mov_b32_e32 v115, v129
	v_mov_b32_e32 v116, v129
	v_mov_b32_e32 v117, v129
	v_mov_b32_e32 v118, v129
	v_mov_b32_e32 v119, v129
	v_readfirstlane_b32 s99, v181
	v_mov_b32_e32 v120, v129
	v_mov_b32_e32 v121, v129
	v_mov_b32_e32 v122, v129
	v_mov_b32_e32 v123, v129
	v_mov_b32_e32 v124, v129
	v_mov_b32_e32 v125, v129
	v_mov_b32_e32 v126, v129
	v_mov_b32_e32 v127, v129
.LBB0_161:
	s_add_i32 s22, s7, 0xfffe8000
	s_and_b32 s22, s22, 0x18000
	s_add_i32 s22, s22, 16
	v_add_u32_e32 v128, s22, v182
	v_add_u32_e32 v176, s22, v184
	v_add_u32_e32 v177, s22, v185
	v_add_u32_e32 v152, v128, v183
	v_add_u32_e32 v156, v176, v183
	v_add_u32_e32 v168, v177, v183
	v_add_u32_e32 v128, v128, v186
	s_and_b32 s98, s7, 0x18000
	s_add_i32 s98, s98, s99
	s_waitcnt vmcnt(8)
	s_waitcnt lgkmcnt(0)
	s_barrier
	ds_read_b128 v[148:151], v152
	ds_read_b128 v[152:155], v152 offset:2048
	ds_read_b128 v[156:159], v156 offset:16384
	ds_read_b128 v[160:163], v168 offset:18432
	ds_read_b128 v[164:167], v168 offset:20480
	ds_read_b128 v[168:171], v168 offset:22528
	ds_read_b128 v[172:175], v128
	ds_read_b128 v[210:213], v128 offset:2048
	v_add_u32_e32 v128, v176, v186
	v_add_u32_e32 v176, v177, v186
	ds_read_b128 v[214:217], v128 offset:16384
	ds_read_b128 v[218:221], v176 offset:18432
	ds_read_b128 v[222:225], v176 offset:20480
	ds_read_b128 v[226:229], v176 offset:22528
	v_lshl_add_u64 v[250:251], v[144:145], 0, s[4:5]
	s_mov_b32 m0, s98
	s_waitcnt lgkmcnt(9)
	v_mfma_f32_32x32x16_bf16 v[112:127], v[148:151], v[156:159], v[112:127]
	s_waitcnt lgkmcnt(8)
	v_mfma_f32_32x32x16_bf16 v[96:111], v[148:151], v[160:163], v[96:111]
	global_load_lds_dwordx4 v[250:251], off
	v_lshl_add_u64 v[250:251], v[146:147], 0, s[4:5]
	s_add_i32 m0, s98, 0x2000
	s_waitcnt lgkmcnt(7)
	v_mfma_f32_32x32x16_bf16 v[48:63], v[148:151], v[164:167], v[48:63]
	s_waitcnt lgkmcnt(6)
	v_mfma_f32_32x32x16_bf16 v[32:47], v[148:151], v[168:171], v[32:47]
	v_mfma_f32_32x32x16_bf16 v[80:95], v[152:155], v[156:159], v[80:95]
	v_mfma_f32_32x32x16_bf16 v[64:79], v[152:155], v[160:163], v[64:79]
	global_load_lds_dwordx4 v[250:251], off
	v_lshl_add_u64 v[250:251], v[140:141], 0, s[4:5]
	s_add_i32 m0, s98, 0x4000
	v_mfma_f32_32x32x16_bf16 v[16:31], v[152:155], v[164:167], v[16:31]
	v_mfma_f32_32x32x16_bf16 v[0:15], v[152:155], v[168:171], v[0:15]
	s_waitcnt lgkmcnt(3)
	v_mfma_f32_32x32x16_bf16 v[112:127], v[172:175], v[214:217], v[112:127]
	s_waitcnt lgkmcnt(2)
	v_mfma_f32_32x32x16_bf16 v[96:111], v[172:175], v[218:221], v[96:111]
	global_load_lds_dwordx4 v[250:251], off
	v_lshl_add_u64 v[250:251], v[142:143], 0, s[4:5]
	s_add_i32 m0, s98, 0x6000
	s_waitcnt lgkmcnt(1)
	v_mfma_f32_32x32x16_bf16 v[48:63], v[172:175], v[222:225], v[48:63]
	s_waitcnt lgkmcnt(0)
	v_mfma_f32_32x32x16_bf16 v[32:47], v[172:175], v[226:229], v[32:47]
	v_mfma_f32_32x32x16_bf16 v[80:95], v[210:213], v[214:217], v[80:95]
	v_mfma_f32_32x32x16_bf16 v[64:79], v[210:213], v[218:221], v[64:79]
	global_load_lds_dwordx4 v[250:251], off
	s_add_u32 s4, s4, 64
	s_addc_u32 s5, s5, 0
	s_add_i32 s7, s7, 0x8000
	s_cmpk_eq_i32 s4, 0x740
	v_mfma_f32_32x32x16_bf16 v[16:31], v[210:213], v[222:225], v[16:31]
	v_mfma_f32_32x32x16_bf16 v[0:15], v[210:213], v[226:229], v[0:15]
	s_cbranch_scc0 .LBB0_161
	s_waitcnt vmcnt(8)
	v_add_u32_e32 v128, v196, v183
	s_waitcnt lgkmcnt(0)
	s_barrier
	ds_read_b128 v[140:143], v128 offset:32768
	ds_read_b128 v[144:147], v128 offset:34816
	v_add_u32_e32 v128, v197, v183
	v_add_u32_e32 v160, v198, v183
	ds_read_b128 v[148:151], v128 offset:49152
	ds_read_b128 v[152:155], v160 offset:51200
	ds_read_b128 v[156:159], v160 offset:53248
	ds_read_b128 v[160:163], v160 offset:55296
	v_add_u32_e32 v128, v196, v186
	ds_read_b128 v[164:167], v128 offset:32768
	ds_read_b128 v[168:171], v128 offset:34816
	v_add_u32_e32 v128, v197, v186
	v_add_u32_e32 v176, v198, v186
	ds_read_b128 v[172:175], v128 offset:49152
	ds_read_b128 v[210:213], v176 offset:51200
	ds_read_b128 v[214:217], v176 offset:53248
	ds_read_b128 v[218:221], v176 offset:55296
	s_waitcnt lgkmcnt(0)
	v_mfma_f32_32x32x16_bf16 v[112:127], v[140:143], v[148:151], v[112:127]
	s_waitcnt vmcnt(4)
	v_add_u32_e32 v128, v193, v186
	s_waitcnt lgkmcnt(0)
	s_barrier
	v_add_u32_e32 v176, v194, v183
	v_mfma_f32_32x32x16_bf16 v[96:111], v[140:143], v[152:155], v[96:111]
	v_mfma_f32_32x32x16_bf16 v[48:63], v[140:143], v[156:159], v[48:63]
	v_mfma_f32_32x32x16_bf16 v[32:47], v[140:143], v[160:163], v[32:47]
	v_mfma_f32_32x32x16_bf16 v[80:95], v[144:147], v[148:151], v[80:95]
	v_mfma_f32_32x32x16_bf16 v[64:79], v[144:147], v[152:155], v[64:79]
	v_add_u32_e32 v152, v194, v186
	v_mfma_f32_32x32x16_bf16 v[16:31], v[144:147], v[156:159], v[16:31]
	v_mfma_f32_32x32x16_bf16 v[0:15], v[144:147], v[160:163], v[0:15]
	ds_read_b128 v[140:143], v128 offset:4096
	ds_read_b128 v[144:147], v128 offset:2048
	ds_read_b128 v[148:151], v128 offset:6144
	ds_read_b128 v[152:155], v152
	v_add_u32_e32 v128, v195, v186
	ds_read_b128 v[156:159], v128 offset:2048
	ds_read_b128 v[160:163], v128
	v_add_u32_e32 v128, v193, v183
	v_mfma_f32_32x32x16_bf16 v[112:127], v[164:167], v[172:175], v[112:127]
	v_mfma_f32_32x32x16_bf16 v[96:111], v[164:167], v[210:213], v[96:111]
	v_mfma_f32_32x32x16_bf16 v[48:63], v[164:167], v[214:217], v[48:63]
	v_mfma_f32_32x32x16_bf16 v[32:47], v[164:167], v[218:221], v[32:47]
	v_mfma_f32_32x32x16_bf16 v[80:95], v[168:171], v[172:175], v[80:95]
	ds_read_b128 v[164:167], v128 offset:4096
	ds_read_b128 v[172:175], v128 offset:2048
	v_mfma_f32_32x32x16_bf16 v[64:79], v[168:171], v[210:213], v[64:79]
	v_mfma_f32_32x32x16_bf16 v[16:31], v[168:171], v[214:217], v[16:31]
	ds_read_b128 v[210:213], v128 offset:6144
	ds_read_b128 v[214:217], v176
	v_add_u32_e32 v128, v195, v183
	ds_read_b128 v[222:225], v128 offset:2048
	ds_read_b128 v[226:229], v128
	v_mfma_f32_32x32x16_bf16 v[0:15], v[168:171], v[218:221], v[0:15]
	s_waitcnt lgkmcnt(0)
	v_mfma_f32_32x32x16_bf16 v[112:127], v[226:229], v[214:217], v[112:127]
	s_waitcnt vmcnt(0)
	v_add_u32_e32 v128, v187, v186
	s_waitcnt lgkmcnt(0)
	s_barrier
	v_add_u32_e32 v176, v188, v183
	v_mfma_f32_32x32x16_bf16 v[96:111], v[226:229], v[172:175], v[96:111]
	v_mfma_f32_32x32x16_bf16 v[48:63], v[226:229], v[164:167], v[48:63]
	v_mfma_f32_32x32x16_bf16 v[32:47], v[226:229], v[210:213], v[32:47]
	v_mfma_f32_32x32x16_bf16 v[80:95], v[222:225], v[214:217], v[80:95]
	v_mfma_f32_32x32x16_bf16 v[64:79], v[222:225], v[172:175], v[64:79]
	v_mfma_f32_32x32x16_bf16 v[16:31], v[222:225], v[164:167], v[16:31]
	v_add_u32_e32 v164, v188, v186
	v_mfma_f32_32x32x16_bf16 v[0:15], v[222:225], v[210:213], v[0:15]
	v_mfma_f32_32x32x16_bf16 v[112:127], v[160:163], v[152:155], v[112:127]
	v_mfma_f32_32x32x16_bf16 v[96:111], v[160:163], v[144:147], v[96:111]
	v_mfma_f32_32x32x16_bf16 v[48:63], v[160:163], v[140:143], v[48:63]
	v_mfma_f32_32x32x16_bf16 v[32:47], v[160:163], v[148:151], v[32:47]
	v_mfma_f32_32x32x16_bf16 v[80:95], v[156:159], v[152:155], v[80:95]
	ds_read_b128 v[152:155], v128 offset:4096
	ds_read_b128 v[160:163], v128 offset:2048
	v_mfma_f32_32x32x16_bf16 v[64:79], v[156:159], v[144:147], v[64:79]
	ds_read_b128 v[144:147], v128 offset:6144
	ds_read_b128 v[164:167], v164
	v_add_u32_e32 v128, v189, v186
	ds_read_b128 v[168:171], v128 offset:2048
	ds_read_b128 v[172:175], v128
	v_add_u32_e32 v128, v187, v183
	v_mfma_f32_32x32x16_bf16 v[16:31], v[156:159], v[140:143], v[16:31]
	ds_read_b128 v[140:143], v128 offset:4096
	ds_read_b128 v[210:213], v128 offset:2048
	ds_read_b128 v[214:217], v128 offset:6144
	ds_read_b128 v[218:221], v176
	v_add_u32_e32 v128, v189, v183
	ds_read_b128 v[222:225], v128 offset:2048
	ds_read_b128 v[226:229], v128
	v_mfma_f32_32x32x16_bf16 v[0:15], v[156:159], v[148:151], v[0:15]
	s_waitcnt lgkmcnt(0)
	v_mfma_f32_32x32x16_bf16 v[112:127], v[226:229], v[218:221], v[112:127]
	s_waitcnt lgkmcnt(0)
	s_cmp_eq_u32 s94, 6
	s_cselect_b64 s[24:25], -1, 0
	s_cmp_lg_u32 s94, 6
	s_barrier
	s_cselect_b64 s[22:23], -1, 0
	s_mov_b64 s[58:59], -1
	v_mfma_f32_32x32x16_bf16 v[96:111], v[226:229], v[210:213], v[96:111]
	v_mfma_f32_32x32x16_bf16 v[48:63], v[226:229], v[140:143], v[48:63]
	v_mfma_f32_32x32x16_bf16 v[32:47], v[226:229], v[214:217], v[32:47]
	v_mfma_f32_32x32x16_bf16 v[80:95], v[222:225], v[218:221], v[80:95]
	v_mfma_f32_32x32x16_bf16 v[64:79], v[222:225], v[210:213], v[64:79]
	v_mov_b32_e32 v211, v133
	s_nop 0
	v_and_b32_e32 v212, 31, v211
	v_ashrrev_i32_e32 v213, 5, v211
	v_mfma_f32_32x32x16_bf16 v[16:31], v[222:225], v[140:143], v[16:31]
	v_add_u32_e32 v140, s6, v190
	v_or_b32_e32 v142, s93, v132
	v_ashrrev_i32_e32 v210, 14, v140
	v_cmp_lt_i32_e64 s[4:5], s55, v142
	v_mfma_f32_32x32x16_bf16 v[0:15], v[222:225], v[214:217], v[0:15]
	v_mfma_f32_32x32x16_bf16 v[112:127], v[172:175], v[164:167], v[112:127]
	v_mfma_f32_32x32x16_bf16 v[96:111], v[172:175], v[160:163], v[96:111]
	v_mfma_f32_32x32x16_bf16 v[48:63], v[172:175], v[152:155], v[48:63]
	v_mfma_f32_32x32x16_bf16 v[32:47], v[172:175], v[144:147], v[32:47]
	v_mfma_f32_32x32x16_bf16 v[80:95], v[168:171], v[164:167], v[80:95]
	v_mfma_f32_32x32x16_bf16 v[64:79], v[168:171], v[160:163], v[64:79]
	v_mfma_f32_32x32x16_bf16 v[16:31], v[168:171], v[152:155], v[16:31]
	v_mfma_f32_32x32x16_bf16 v[0:15], v[168:171], v[144:147], v[0:15]
	s_and_saveexec_b64 s[48:49], s[4:5]
	s_cbranch_execz .LBB0_197
	s_cmp_lt_i32 s94, 8
	s_cbranch_scc1 .LBB0_165
	s_cmp_lg_u32 s94, 8
	s_mov_b64 s[6:7], -1
	s_cselect_b64 s[58:59], -1, 0
	s_cbranch_execz .LBB0_166
	s_branch .LBB0_167

.LBB0_674:
	s_ashr_i32 s8, s10, 31
	s_lshr_b32 s8, s8, 30
	s_add_i32 s8, s10, s8
	s_ashr_i32 s9, s8, 2
	s_add_i32 s11, s9, s56
	s_lshl_b32 s11, s11, 8
	v_add_u32_e32 v4, s11, v159
	s_and_b32 s8, s8, 0xfffffc
	v_ashrrev_i32_e32 v5, 31, v4
	s_sub_i32 s8, s10, s8
	v_lshlrev_b64 v[4:5], 11, v[4:5]
	s_lshl_b32 s12, s8, 8
	v_lshl_add_u64 v[6:7], s[48:49], 0, v[4:5]
	v_readfirstlane_b32 s8, v161
	v_lshl_add_u64 v[6:7], v[6:7], 0, v[154:155]
	s_mov_b32 m0, s8
	s_barrier
	global_load_lds_dwordx4 v[6:7], off
	v_add_u32_e32 v6, s11, v160
	v_ashrrev_i32_e32 v7, 31, v6
	v_add_u32_e32 v0, s12, v159
	v_lshlrev_b64 v[6:7], 11, v[6:7]
	v_ashrrev_i32_e32 v1, 31, v0
	v_add_u32_e32 v2, s12, v160
	v_lshl_add_u64 v[8:9], s[48:49], 0, v[6:7]
	v_readfirstlane_b32 s8, v179
	v_lshlrev_b64 v[0:1], 11, v[0:1]
	v_ashrrev_i32_e32 v3, 31, v2
	v_lshl_add_u64 v[8:9], v[8:9], 0, v[154:155]
	s_mov_b32 m0, s8
	v_readfirstlane_b32 s8, v180
	v_lshl_add_u64 v[0:1], v[146:147], 0, v[0:1]
	v_lshlrev_b64 v[2:3], 11, v[2:3]
	global_load_lds_dwordx4 v[8:9], off
	s_mov_b32 m0, s8
	v_readfirstlane_b32 s8, v181
	v_lshl_add_u64 v[2:3], v[146:147], 0, v[2:3]
	global_load_lds_dwordx4 v[0:1], off
	s_mov_b32 m0, s8
	v_lshl_add_u64 v[8:9], v[148:149], 0, v[4:5]
	v_readfirstlane_b32 s8, v182
	global_load_lds_dwordx4 v[2:3], off
	v_lshl_add_u64 v[10:11], v[8:9], 0, s[0:1]
	s_mov_b32 m0, s8
	v_readfirstlane_b32 s8, v183
	global_load_lds_dwordx4 v[10:11], off
	v_lshl_add_u64 v[10:11], v[148:149], 0, v[6:7]
	v_lshl_add_u64 v[12:13], v[10:11], 0, s[0:1]
	s_mov_b32 m0, s8
	v_readfirstlane_b32 s8, v184
	global_load_lds_dwordx4 v[12:13], off
	v_lshl_add_u64 v[12:13], v[0:1], 0, 64
	s_mov_b32 m0, s8
	v_readfirstlane_b32 s8, v185
	global_load_lds_dwordx4 v[12:13], off
	v_lshl_add_u64 v[12:13], v[2:3], 0, 64
	s_mov_b32 m0, s8
	v_readfirstlane_b32 s8, v186
	global_load_lds_dwordx4 v[12:13], off
	v_lshl_add_u64 v[8:9], v[8:9], 0, s[4:5]
	s_mov_b32 m0, s8
	v_readfirstlane_b32 s8, v187
	global_load_lds_dwordx4 v[8:9], off
	v_lshl_add_u64 v[8:9], v[10:11], 0, s[4:5]
	s_mov_b32 m0, s8
	v_readfirstlane_b32 s8, v188
	global_load_lds_dwordx4 v[8:9], off
	v_lshl_add_u64 v[0:1], v[0:1], 0, s[6:7]
	s_mov_b32 m0, s8
	v_readfirstlane_b32 s8, v189
	global_load_lds_dwordx4 v[0:1], off
	v_lshl_add_u64 v[0:1], v[2:3], 0, s[6:7]
	s_mov_b32 m0, s8
	s_lshl_b32 s8, s10, 8
	global_load_lds_dwordx4 v[0:1], off
	v_add_u32_e32 v0, s8, v159
	s_lshl_b32 s9, s9, 10
	v_subrev_u32_e32 v0, s9, v0
	v_ashrrev_i32_e32 v1, 31, v0
	v_lshlrev_b64 v[0:1], 11, v[0:1]
	v_lshl_add_u64 v[128:129], v[150:151], 0, v[0:1]
	v_add_u32_e32 v0, s8, v160
	v_subrev_u32_e32 v0, s9, v0
	v_ashrrev_i32_e32 v1, 31, v0
	v_lshlrev_b64 v[0:1], 11, v[0:1]
	v_lshl_add_u64 v[130:131], v[150:151], 0, v[0:1]
	v_lshl_add_u64 v[132:133], v[152:153], 0, v[4:5]
	v_lshl_add_u64 v[134:135], v[152:153], 0, v[6:7]
	s_mov_b64 s[8:9], 0
	s_mov_b32 s13, 0x18000
	v_mov_b32_e32 v0, 0
	v_mov_b32_e32 v1, v145
	v_mov_b32_e32 v2, v145
	v_mov_b32_e32 v3, v145
	v_mov_b32_e32 v4, v145
	v_mov_b32_e32 v5, v145
	v_mov_b32_e32 v6, v145
	v_mov_b32_e32 v7, v145
	v_mov_b32_e32 v8, v145
	v_mov_b32_e32 v9, v145
	v_mov_b32_e32 v10, v145
	v_mov_b32_e32 v11, v145
	v_mov_b32_e32 v12, v145
	v_mov_b32_e32 v13, v145
	v_mov_b32_e32 v14, v145
	v_mov_b32_e32 v15, v145
	v_mov_b32_e32 v16, 0
	v_mov_b32_e32 v17, v145
	v_mov_b32_e32 v18, v145
	v_mov_b32_e32 v19, v145
	v_mov_b32_e32 v20, v145
	v_mov_b32_e32 v21, v145
	v_mov_b32_e32 v22, v145
	v_mov_b32_e32 v23, v145
	v_mov_b32_e32 v24, v145
	v_mov_b32_e32 v25, v145
	v_mov_b32_e32 v26, v145
	v_mov_b32_e32 v27, v145
	v_mov_b32_e32 v28, v145
	v_mov_b32_e32 v29, v145
	v_mov_b32_e32 v30, v145
	v_mov_b32_e32 v31, v145
	v_mov_b32_e32 v64, 0
	v_mov_b32_e32 v65, v145
	v_mov_b32_e32 v66, v145
	v_mov_b32_e32 v67, v145
	v_mov_b32_e32 v68, v145
	v_mov_b32_e32 v69, v145
	v_mov_b32_e32 v70, v145
	v_mov_b32_e32 v71, v145
	v_mov_b32_e32 v72, v145
	v_mov_b32_e32 v73, v145
	v_mov_b32_e32 v74, v145
	v_mov_b32_e32 v75, v145
	v_mov_b32_e32 v76, v145
	v_mov_b32_e32 v77, v145
	v_mov_b32_e32 v78, v145
	v_mov_b32_e32 v79, v145
	v_mov_b32_e32 v80, 0
	v_mov_b32_e32 v81, v145
	v_mov_b32_e32 v82, v145
	v_mov_b32_e32 v83, v145
	v_mov_b32_e32 v84, v145
	v_mov_b32_e32 v85, v145
	v_mov_b32_e32 v86, v145
	v_mov_b32_e32 v87, v145
	v_mov_b32_e32 v88, v145
	v_mov_b32_e32 v89, v145
	v_mov_b32_e32 v90, v145
	v_mov_b32_e32 v91, v145
	v_mov_b32_e32 v92, v145
	v_mov_b32_e32 v93, v145
	v_mov_b32_e32 v94, v145
	v_mov_b32_e32 v95, v145
	v_mov_b32_e32 v32, 0
	v_mov_b32_e32 v33, v145
	v_mov_b32_e32 v34, v145
	v_mov_b32_e32 v35, v145
	v_mov_b32_e32 v36, v145
	v_mov_b32_e32 v37, v145
	v_mov_b32_e32 v38, v145
	v_mov_b32_e32 v39, v145
	v_mov_b32_e32 v40, v145
	v_mov_b32_e32 v41, v145
	v_mov_b32_e32 v42, v145
	v_mov_b32_e32 v43, v145
	v_mov_b32_e32 v44, v145
	v_mov_b32_e32 v45, v145
	v_mov_b32_e32 v46, v145
	v_mov_b32_e32 v47, v145
	v_mov_b32_e32 v48, 0
	v_mov_b32_e32 v49, v145
	v_mov_b32_e32 v50, v145
	v_mov_b32_e32 v51, v145
	v_mov_b32_e32 v52, v145
	v_mov_b32_e32 v53, v145
	v_mov_b32_e32 v54, v145
	v_mov_b32_e32 v55, v145
	v_mov_b32_e32 v56, v145
	v_mov_b32_e32 v57, v145
	v_mov_b32_e32 v58, v145
	v_mov_b32_e32 v59, v145
	v_mov_b32_e32 v60, v145
	v_mov_b32_e32 v61, v145
	v_mov_b32_e32 v62, v145
	v_mov_b32_e32 v63, v145
	v_mov_b32_e32 v96, 0
	v_mov_b32_e32 v97, v145
	v_mov_b32_e32 v98, v145
	v_mov_b32_e32 v99, v145
	v_mov_b32_e32 v100, v145
	v_mov_b32_e32 v101, v145
	v_mov_b32_e32 v102, v145
	v_mov_b32_e32 v103, v145
	v_mov_b32_e32 v104, v145
	v_mov_b32_e32 v105, v145
	v_mov_b32_e32 v106, v145
	v_mov_b32_e32 v107, v145
	v_mov_b32_e32 v108, v145
	v_mov_b32_e32 v109, v145
	v_mov_b32_e32 v110, v145
	v_mov_b32_e32 v111, v145
	v_mov_b32_e32 v112, 0
	v_mov_b32_e32 v113, v145
	v_mov_b32_e32 v114, v145
	v_mov_b32_e32 v115, v145
	v_mov_b32_e32 v116, v145
	v_mov_b32_e32 v117, v145
	v_mov_b32_e32 v118, v145
	v_mov_b32_e32 v119, v145
	v_readfirstlane_b32 s99, v161
	v_mov_b32_e32 v120, v145
	v_mov_b32_e32 v121, v145
	v_mov_b32_e32 v122, v145
	v_mov_b32_e32 v123, v145
	v_mov_b32_e32 v124, v145
	v_mov_b32_e32 v125, v145
	v_mov_b32_e32 v126, v145
	v_mov_b32_e32 v127, v145
.LBB0_675:
	s_add_i32 s14, s13, 0xfffe8000
	s_and_b32 s14, s14, 0x18000
	s_add_i32 s14, s14, 16
	v_add_u32_e32 v144, s14, v162
	v_add_u32_e32 v156, s14, v164
	v_add_u32_e32 v140, v144, v163
	v_add_u32_e32 v157, v156, v163
	v_add_u32_e32 v190, s14, v166
	v_add_u32_e32 v144, v144, v167
	s_and_b32 s98, s13, 0x18000
	s_add_i32 s98, s98, s99
	s_waitcnt vmcnt(8)
	s_waitcnt lgkmcnt(0)
	s_barrier
	ds_read_b128 v[136:139], v140
	ds_read_b128 v[140:143], v140 offset:2048
	v_add_u32_e32 v192, v190, v163
	ds_read_b128 v[198:201], v157 offset:16384
	ds_read_b128 v[202:205], v192 offset:18432
	ds_read_b128 v[208:211], v192 offset:20480
	ds_read_b128 v[212:215], v192 offset:22528
	ds_read_b128 v[216:219], v144
	ds_read_b128 v[220:223], v144 offset:2048
	v_add_u32_e32 v144, v156, v167
	v_add_u32_e32 v156, v190, v167
	ds_read_b128 v[224:227], v144 offset:16384
	ds_read_b128 v[228:231], v156 offset:18432
	ds_read_b128 v[232:235], v156 offset:20480
	ds_read_b128 v[236:239], v156 offset:22528
	v_lshl_add_u64 v[250:251], v[132:133], 0, s[8:9]
	s_mov_b32 m0, s98
	s_waitcnt lgkmcnt(9)
	v_mfma_f32_32x32x16_bf16 v[112:127], v[136:139], v[198:201], v[112:127]
	s_waitcnt lgkmcnt(8)
	v_mfma_f32_32x32x16_bf16 v[96:111], v[136:139], v[202:205], v[96:111]
	global_load_lds_dwordx4 v[250:251], off
	v_lshl_add_u64 v[250:251], v[134:135], 0, s[8:9]
	s_add_i32 m0, s98, 0x2000
	s_waitcnt lgkmcnt(7)
	v_mfma_f32_32x32x16_bf16 v[48:63], v[136:139], v[208:211], v[48:63]
	s_waitcnt lgkmcnt(6)
	v_mfma_f32_32x32x16_bf16 v[32:47], v[136:139], v[212:215], v[32:47]
	v_mfma_f32_32x32x16_bf16 v[80:95], v[140:143], v[198:201], v[80:95]
	v_mfma_f32_32x32x16_bf16 v[64:79], v[140:143], v[202:205], v[64:79]
	global_load_lds_dwordx4 v[250:251], off
	v_lshl_add_u64 v[250:251], v[128:129], 0, s[8:9]
	s_add_i32 m0, s98, 0x4000
	v_mfma_f32_32x32x16_bf16 v[16:31], v[140:143], v[208:211], v[16:31]
	v_mfma_f32_32x32x16_bf16 v[0:15], v[140:143], v[212:215], v[0:15]
	s_waitcnt lgkmcnt(3)
	v_mfma_f32_32x32x16_bf16 v[112:127], v[216:219], v[224:227], v[112:127]
	s_waitcnt lgkmcnt(2)
	v_mfma_f32_32x32x16_bf16 v[96:111], v[216:219], v[228:231], v[96:111]
	global_load_lds_dwordx4 v[250:251], off
	v_lshl_add_u64 v[250:251], v[130:131], 0, s[8:9]
	s_add_i32 m0, s98, 0x6000
	s_waitcnt lgkmcnt(1)
	v_mfma_f32_32x32x16_bf16 v[48:63], v[216:219], v[232:235], v[48:63]
	s_waitcnt lgkmcnt(0)
	v_mfma_f32_32x32x16_bf16 v[32:47], v[216:219], v[236:239], v[32:47]
	v_mfma_f32_32x32x16_bf16 v[80:95], v[220:223], v[224:227], v[80:95]
	v_mfma_f32_32x32x16_bf16 v[64:79], v[220:223], v[228:231], v[64:79]
	global_load_lds_dwordx4 v[250:251], off
	s_add_u32 s8, s8, 64
	s_addc_u32 s9, s9, 0
	s_add_i32 s13, s13, 0x8000
	s_cmpk_lg_i32 s8, 0x740
	v_mfma_f32_32x32x16_bf16 v[16:31], v[220:223], v[232:235], v[16:31]
	v_mfma_f32_32x32x16_bf16 v[0:15], v[220:223], v[236:239], v[0:15]
	s_cbranch_scc1 .LBB0_675
	s_waitcnt vmcnt(8)
	v_add_u32_e32 v132, v176, v163
	v_add_u32_e32 v136, v177, v163
	v_add_u32_e32 v144, v178, v163
	s_waitcnt lgkmcnt(0)
	s_barrier
	ds_read_b128 v[128:131], v132 offset:32768
	ds_read_b128 v[132:135], v132 offset:34816
	ds_read_b128 v[136:139], v136 offset:49152
	ds_read_b128 v[140:143], v144 offset:51200
	ds_read_b128 v[198:201], v144 offset:53248
	ds_read_b128 v[202:205], v144 offset:55296
	v_add_u32_e32 v144, v176, v167
	ds_read_b128 v[208:211], v144 offset:32768
	ds_read_b128 v[212:215], v144 offset:34816
	v_add_u32_e32 v144, v177, v167
	v_add_u32_e32 v156, v178, v167
	ds_read_b128 v[216:219], v144 offset:49152
	ds_read_b128 v[220:223], v156 offset:51200
	ds_read_b128 v[224:227], v156 offset:53248
	ds_read_b128 v[228:231], v156 offset:55296
	s_waitcnt lgkmcnt(0)
	v_mfma_f32_32x32x16_bf16 v[112:127], v[128:131], v[136:139], v[112:127]
	s_waitcnt vmcnt(4)
	v_add_u32_e32 v144, v173, v163
	s_waitcnt lgkmcnt(0)
	s_barrier
	v_add_u32_e32 v156, v174, v163
	v_mfma_f32_32x32x16_bf16 v[96:111], v[128:131], v[140:143], v[96:111]
	v_mfma_f32_32x32x16_bf16 v[48:63], v[128:131], v[198:201], v[48:63]
	v_mfma_f32_32x32x16_bf16 v[32:47], v[128:131], v[202:205], v[32:47]
	v_mfma_f32_32x32x16_bf16 v[80:95], v[132:135], v[136:139], v[80:95]
	v_add_u32_e32 v136, v175, v167
	v_mfma_f32_32x32x16_bf16 v[64:79], v[132:135], v[140:143], v[64:79]
	v_mfma_f32_32x32x16_bf16 v[16:31], v[132:135], v[198:201], v[16:31]
	v_mfma_f32_32x32x16_bf16 v[0:15], v[132:135], v[202:205], v[0:15]
	v_add_u32_e32 v132, v173, v167
	v_add_u32_e32 v133, v174, v167
	ds_read_b128 v[198:201], v132 offset:4096
	ds_read_b128 v[128:131], v132 offset:2048
	ds_read_b128 v[202:205], v132 offset:6144
	ds_read_b128 v[132:135], v133
	v_mfma_f32_32x32x16_bf16 v[112:127], v[208:211], v[216:219], v[112:127]
	v_mfma_f32_32x32x16_bf16 v[96:111], v[208:211], v[220:223], v[96:111]
	v_mfma_f32_32x32x16_bf16 v[48:63], v[208:211], v[224:227], v[48:63]
	v_mfma_f32_32x32x16_bf16 v[32:47], v[208:211], v[228:231], v[32:47]
	ds_read_b128 v[208:211], v136 offset:2048
	ds_read_b128 v[136:139], v136
	v_mfma_f32_32x32x16_bf16 v[80:95], v[212:215], v[216:219], v[80:95]
	ds_read_b128 v[140:143], v144 offset:4096
	ds_read_b128 v[216:219], v144 offset:2048
	v_mfma_f32_32x32x16_bf16 v[64:79], v[212:215], v[220:223], v[64:79]
	v_mfma_f32_32x32x16_bf16 v[16:31], v[212:215], v[224:227], v[16:31]
	ds_read_b128 v[220:223], v144 offset:6144
	ds_read_b128 v[224:227], v156
	v_add_u32_e32 v144, v175, v163
	ds_read_b128 v[232:235], v144 offset:2048
	ds_read_b128 v[236:239], v144
	v_mfma_f32_32x32x16_bf16 v[0:15], v[212:215], v[228:231], v[0:15]
	s_waitcnt lgkmcnt(0)
	v_mfma_f32_32x32x16_bf16 v[112:127], v[236:239], v[224:227], v[112:127]
	s_waitcnt vmcnt(0)
	v_add_u32_e32 v144, v168, v163
	s_waitcnt lgkmcnt(0)
	s_barrier
	v_add_u32_e32 v156, v169, v163
	v_mfma_f32_32x32x16_bf16 v[80:95], v[232:235], v[224:227], v[80:95]
	v_mfma_f32_32x32x16_bf16 v[96:111], v[236:239], v[216:219], v[96:111]
	v_mfma_f32_32x32x16_bf16 v[48:63], v[236:239], v[140:143], v[48:63]
	v_mfma_f32_32x32x16_bf16 v[32:47], v[236:239], v[220:223], v[32:47]
	v_mfma_f32_32x32x16_bf16 v[64:79], v[232:235], v[216:219], v[64:79]
	v_mfma_f32_32x32x16_bf16 v[16:31], v[232:235], v[140:143], v[16:31]
	v_add_u32_e32 v140, v170, v167
	v_mfma_f32_32x32x16_bf16 v[0:15], v[232:235], v[220:223], v[0:15]
	v_mfma_f32_32x32x16_bf16 v[112:127], v[136:139], v[132:135], v[112:127]
	v_mfma_f32_32x32x16_bf16 v[80:95], v[208:211], v[132:135], v[80:95]
	v_add_u32_e32 v132, v168, v167
	v_add_u32_e32 v133, v169, v167
	v_mfma_f32_32x32x16_bf16 v[96:111], v[136:139], v[128:131], v[96:111]
	v_mfma_f32_32x32x16_bf16 v[48:63], v[136:139], v[198:201], v[48:63]
	v_mfma_f32_32x32x16_bf16 v[32:47], v[136:139], v[202:205], v[32:47]
	ds_read_b128 v[136:139], v132 offset:4096
	ds_read_b128 v[212:215], v132 offset:2048
	v_mfma_f32_32x32x16_bf16 v[64:79], v[208:211], v[128:131], v[64:79]
	ds_read_b128 v[128:131], v132 offset:6144
	ds_read_b128 v[216:219], v133
	ds_read_b128 v[132:135], v140 offset:2048
	ds_read_b128 v[140:143], v140
	v_mfma_f32_32x32x16_bf16 v[16:31], v[208:211], v[198:201], v[16:31]
	ds_read_b128 v[198:201], v144 offset:4096
	ds_read_b128 v[220:223], v144 offset:2048
	ds_read_b128 v[224:227], v144 offset:6144
	ds_read_b128 v[228:231], v156
	v_add_u32_e32 v144, v170, v163
	ds_read_b128 v[232:235], v144 offset:2048
	ds_read_b128 v[236:239], v144
	v_mfma_f32_32x32x16_bf16 v[0:15], v[208:211], v[202:205], v[0:15]
	s_waitcnt lgkmcnt(0)
	v_mfma_f32_32x32x16_bf16 v[112:127], v[236:239], v[228:231], v[112:127]
	v_mov_b32_e32 v144, v158
	s_waitcnt lgkmcnt(0)
	s_barrier
	v_add_u32_e32 v156, s11, v171
	v_or_b32_e32 v202, s12, v165
	v_mfma_f32_32x32x16_bf16 v[96:111], v[236:239], v[220:223], v[96:111]
	v_and_b32_e32 v190, 31, v144
	v_lshlrev_b32_e32 v192, 5, v144
	v_and_b32_e32 v192, 0xfffffc00, v192
	v_lshlrev_b32_e32 v190, 2, v190
	v_add3_u32 v190, v172, v192, v190
	v_ashrrev_i32_e32 v157, 31, v156
	v_lshlrev_b64 v[204:205], 12, v[156:157]
	v_mfma_f32_32x32x16_bf16 v[80:95], v[232:235], v[228:231], v[80:95]
	v_ashrrev_i32_e32 v203, 31, v202
	v_lshl_add_u64 v[156:157], s[68:69], 0, v[204:205]
	v_lshlrev_b64 v[202:203], 2, v[202:203]
	v_lshl_add_u64 v[156:157], v[156:157], 0, v[202:203]
	s_add_i32 s10, s10, s50
	s_cmp_ge_i32 s10, s51
	v_mfma_f32_32x32x16_bf16 v[64:79], v[232:235], v[220:223], v[64:79]
	v_mfma_f32_32x32x16_bf16 v[112:127], v[140:143], v[216:219], v[112:127]
	v_mfma_f32_32x32x16_bf16 v[96:111], v[140:143], v[212:215], v[96:111]
	s_nop 11
	ds_write2_b32 v190, v112, v96 offset1:32
	ds_write2_b32 v190, v113, v97 offset0:64 offset1:96
	ds_write2_b32 v190, v114, v98 offset0:128 offset1:160
	ds_write2_b32 v190, v115, v99 offset0:192 offset1:224
	v_mfma_f32_32x32x16_bf16 v[80:95], v[132:135], v[216:219], v[80:95]
	v_add_u32_e32 v96, 0x800, v190
	ds_write2_b32 v96, v116, v100 offset1:32
	ds_write2_b32 v96, v117, v101 offset0:64 offset1:96
	ds_write2_b32 v96, v118, v102 offset0:128 offset1:160
	ds_write2_b32 v96, v119, v103 offset0:192 offset1:224
	v_add_u32_e32 v96, 0x1000, v190
	ds_write2_b32 v96, v120, v104 offset1:32
	ds_write2_b32 v96, v121, v105 offset0:64 offset1:96
	ds_write2_b32 v96, v122, v106 offset0:128 offset1:160
	ds_write2_b32 v96, v123, v107 offset0:192 offset1:224
	v_add_u32_e32 v96, 0x1800, v190
	v_mfma_f32_32x32x16_bf16 v[64:79], v[132:135], v[212:215], v[64:79]
	ds_write2_b32 v96, v124, v108 offset1:32
	ds_write2_b32 v96, v125, v109 offset0:64 offset1:96
	ds_write2_b32 v96, v126, v110 offset0:128 offset1:160
	ds_write2_b32 v96, v127, v111 offset0:192 offset1:224
	v_add_u32_e32 v96, 0x2000, v190
	s_nop 6
	ds_write2_b32 v96, v80, v64 offset1:32
	ds_write2_b32 v96, v81, v65 offset0:64 offset1:96
	ds_write2_b32 v96, v82, v66 offset0:128 offset1:160
	ds_write2_b32 v96, v83, v67 offset0:192 offset1:224
	v_add_u32_e32 v64, 0x2800, v190
	ds_write2_b32 v64, v84, v68 offset1:32
	ds_write2_b32 v64, v85, v69 offset0:64 offset1:96
	ds_write2_b32 v64, v86, v70 offset0:128 offset1:160
	ds_write2_b32 v64, v87, v71 offset0:192 offset1:224
	v_add_u32_e32 v64, 0x3000, v190
	ds_write2_b32 v64, v88, v72 offset1:32
	ds_write2_b32 v64, v89, v73 offset0:64 offset1:96
	ds_write2_b32 v64, v90, v74 offset0:128 offset1:160
	ds_write2_b32 v64, v91, v75 offset0:192 offset1:224
	v_add_u32_e32 v64, 0x3800, v190
	ds_write2_b32 v64, v92, v76 offset1:32
	ds_write2_b32 v64, v93, v77 offset0:64 offset1:96
	ds_write2_b32 v64, v94, v78 offset0:128 offset1:160
	ds_write2_b32 v64, v95, v79 offset0:192 offset1:224
	v_ashrrev_i32_e32 v70, 4, v144
	v_lshlrev_b32_e32 v64, 4, v144
	v_and_b32_e32 v144, 0xf0, v64
	v_ashrrev_i32_e32 v71, 31, v70
	v_add_u32_e32 v94, 4, v70
	v_lshl_add_u64 v[66:67], v[156:157], 0, v[144:145]
	v_lshlrev_b64 v[92:93], 12, v[70:71]
	v_ashrrev_i32_e32 v95, 31, v94
	v_lshl_add_u64 v[64:65], v[66:67], 0, v[92:93]
	v_lshlrev_b64 v[96:97], 12, v[94:95]
	global_load_dwordx4 v[72:75], v[64:65], off
	v_lshl_add_u64 v[64:65], v[66:67], 0, v[96:97]
	v_add_u32_e32 v98, 8, v70
	global_load_dwordx4 v[76:79], v[64:65], off
	v_ashrrev_i32_e32 v99, 31, v98
	v_add_u32_e32 v102, 12, v70
	v_lshlrev_b64 v[100:101], 12, v[98:99]
	v_ashrrev_i32_e32 v103, 31, v102
	v_lshl_add_u64 v[64:65], v[66:67], 0, v[100:101]
	v_lshlrev_b64 v[104:105], 12, v[102:103]
	global_load_dwordx4 v[80:83], v[64:65], off
	v_lshl_add_u64 v[64:65], v[66:67], 0, v[104:105]
	global_load_dwordx4 v[84:87], v[64:65], off
	v_lshl_add_u64 v[64:65], s[66:67], 0, v[204:205]
	v_add_u32_e32 v190, v172, v144
	v_lshl_add_u64 v[64:65], v[64:65], 0, v[202:203]
	v_lshl_add_u32 v71, v70, 8, v190
	v_lshl_add_u64 v[68:69], v[64:65], 0, v[144:145]
	ds_read_b128 v[88:91], v71
	v_lshl_add_u32 v71, v94, 8, v190
	v_lshl_add_u64 v[106:107], v[68:69], 0, v[92:93]
	ds_read_b128 v[92:95], v71
	v_lshl_add_u32 v71, v98, 8, v190
	v_lshl_add_u64 v[96:97], v[68:69], 0, v[96:97]
	v_lshl_add_u64 v[98:99], v[68:69], 0, v[100:101]
	v_add_u32_e32 v100, 28, v70
	v_ashrrev_i32_e32 v101, 31, v100
	v_mfma_f32_32x32x16_bf16 v[48:63], v[236:239], v[198:201], v[48:63]
	v_add_u32_e32 v108, 40, v70
	v_add_u32_e32 v110, 44, v70
	v_ashrrev_i32_e32 v109, 31, v108
	v_ashrrev_i32_e32 v111, 31, v110
	v_lshlrev_b64 v[116:117], 12, v[108:109]
	v_lshlrev_b64 v[118:119], 12, v[110:111]
	s_waitcnt vmcnt(0) lgkmcnt(0)
	v_pk_add_f32 v[72:73], v[72:73], v[88:89]
	v_pk_add_f32 v[74:75], v[74:75], v[90:91]
	ds_read_b128 v[88:91], v71
	v_lshl_add_u32 v71, v102, 8, v190
	v_pk_add_f32 v[76:77], v[76:77], v[92:93]
	v_pk_add_f32 v[78:79], v[78:79], v[94:95]
	ds_read_b128 v[92:95], v71
	v_lshlrev_b64 v[102:103], 12, v[100:101]
	v_mfma_f32_32x32x16_bf16 v[32:47], v[236:239], v[224:227], v[32:47]
	v_lshl_add_u32 v100, v100, 8, v190
	s_waitcnt lgkmcnt(1)
	v_add_f32_e64 v80, v80, v88
	v_add_f32_e64 v81, v81, v89
	v_lshl_add_u64 v[88:89], v[68:69], 0, v[104:105]
	v_pk_add_f32 v[82:83], v[82:83], v[90:91]
	s_waitcnt lgkmcnt(0)
	v_pk_add_f32 v[84:85], v[84:85], v[92:93]
	v_pk_add_f32 v[86:87], v[86:87], v[94:95]
	global_store_dwordx4 v[106:107], v[72:75], off
	global_store_dwordx4 v[96:97], v[76:79], off
	global_store_dwordx4 v[98:99], v[80:83], off
	global_store_dwordx4 v[88:89], v[84:87], off
	v_add_u32_e32 v88, 16, v70
	v_ashrrev_i32_e32 v89, 31, v88
	v_add_u32_e32 v92, 20, v70
	v_add_u32_e32 v96, 24, v70
	v_lshlrev_b64 v[90:91], 12, v[88:89]
	v_ashrrev_i32_e32 v93, 31, v92
	v_ashrrev_i32_e32 v97, 31, v96
	v_lshl_add_u64 v[72:73], v[66:67], 0, v[90:91]
	v_lshlrev_b64 v[94:95], 12, v[92:93]
	v_lshlrev_b64 v[98:99], 12, v[96:97]
	v_lshl_add_u64 v[76:77], v[66:67], 0, v[94:95]
	v_lshl_add_u64 v[80:81], v[66:67], 0, v[98:99]
	global_load_dwordx4 v[72:75], v[72:73], off
	v_lshl_add_u64 v[84:85], v[66:67], 0, v[102:103]
	global_load_dwordx4 v[76:79], v[76:77], off
	v_lshl_add_u32 v71, v88, 8, v190
	global_load_dwordx4 v[80:83], v[80:81], off
	v_lshl_add_u32 v92, v92, 8, v190
	global_load_dwordx4 v[84:87], v[84:85], off
	v_lshl_add_u32 v96, v96, 8, v190
	v_lshl_add_u64 v[120:121], v[68:69], 0, v[90:91]
	ds_read_b128 v[88:91], v71
	v_lshl_add_u64 v[122:123], v[68:69], 0, v[94:95]
	v_lshl_add_u64 v[124:125], v[68:69], 0, v[98:99]
	v_lshl_add_u64 v[126:127], v[68:69], 0, v[102:103]
	ds_read_b128 v[92:95], v92
	ds_read_b128 v[96:99], v96
	ds_read_b128 v[100:103], v100
	v_add_u32_e32 v104, 32, v70
	v_add_u32_e32 v106, 36, v70
	v_ashrrev_i32_e32 v105, 31, v104
	v_ashrrev_i32_e32 v107, 31, v106
	v_lshlrev_b64 v[112:113], 12, v[104:105]
	v_mfma_f32_32x32x16_bf16 v[48:63], v[140:143], v[136:139], v[48:63]
	v_lshlrev_b64 v[114:115], 12, v[106:107]
	v_lshl_add_u32 v71, v106, 8, v190
	s_waitcnt vmcnt(3) lgkmcnt(3)
	v_add_f32_e64 v72, v72, v88
	v_add_f32_e64 v73, v73, v89
	v_pk_add_f32 v[74:75], v[74:75], v[90:91]
	v_mfma_f32_32x32x16_bf16 v[32:47], v[140:143], v[128:131], v[32:47]
	v_lshl_add_u64 v[140:141], v[66:67], 0, v[112:113]
	s_waitcnt vmcnt(2) lgkmcnt(2)
	v_add_f32_e64 v76, v76, v92
	v_add_f32_e64 v77, v77, v93
	v_add_f32_e64 v78, v78, v94
	v_add_f32_e64 v79, v79, v95
	s_waitcnt vmcnt(1) lgkmcnt(1)
	v_pk_add_f32 v[80:81], v[80:81], v[96:97]
	v_pk_add_f32 v[82:83], v[82:83], v[98:99]
	s_waitcnt vmcnt(0) lgkmcnt(0)
	v_pk_add_f32 v[84:85], v[84:85], v[100:101]
	v_pk_add_f32 v[86:87], v[86:87], v[102:103]
	global_store_dwordx4 v[120:121], v[72:75], off
	global_store_dwordx4 v[122:123], v[76:79], off
	global_store_dwordx4 v[124:125], v[80:83], off
	global_store_dwordx4 v[126:127], v[84:87], off
	global_load_dwordx4 v[72:75], v[140:141], off
	v_lshl_add_u64 v[76:77], v[66:67], 0, v[114:115]
	v_lshl_add_u64 v[80:81], v[66:67], 0, v[116:117]
	v_lshl_add_u64 v[84:85], v[66:67], 0, v[118:119]
	global_load_dwordx4 v[76:79], v[76:77], off
	v_mfma_f32_32x32x16_bf16 v[16:31], v[232:235], v[198:201], v[16:31]
	global_load_dwordx4 v[80:83], v[80:81], off
	v_add_u32_e32 v120, 48, v70
	global_load_dwordx4 v[84:87], v[84:85], off
	v_add_u32_e32 v122, 52, v70
	v_add_u32_e32 v124, 56, v70
	v_add_u32_e32 v126, 60, v70
	v_lshl_add_u32 v70, v104, 8, v190
	v_lshl_add_u32 v96, v108, 8, v190
	v_lshl_add_u32 v100, v110, 8, v190
	ds_read_b128 v[88:91], v70
	ds_read_b128 v[92:95], v71
	ds_read_b128 v[96:99], v96
	ds_read_b128 v[100:103], v100
	v_ashrrev_i32_e32 v121, 31, v120
	v_ashrrev_i32_e32 v123, 31, v122
	v_ashrrev_i32_e32 v125, 31, v124
	v_ashrrev_i32_e32 v127, 31, v126
	v_lshlrev_b64 v[104:105], 12, v[120:121]
	v_lshl_add_u64 v[112:113], v[68:69], 0, v[112:113]
	v_mfma_f32_32x32x16_bf16 v[16:31], v[132:135], v[136:139], v[16:31]
	v_lshlrev_b64 v[106:107], 12, v[122:123]
	v_lshlrev_b64 v[108:109], 12, v[124:125]
	v_lshlrev_b64 v[110:111], 12, v[126:127]
	v_lshl_add_u64 v[114:115], v[68:69], 0, v[114:115]
	v_lshl_add_u64 v[116:117], v[68:69], 0, v[116:117]
	v_lshl_add_u64 v[118:119], v[68:69], 0, v[118:119]
	v_lshl_add_u64 v[136:137], v[66:67], 0, v[104:105]
	v_mfma_f32_32x32x16_bf16 v[0:15], v[232:235], v[224:227], v[0:15]
	s_waitcnt vmcnt(3) lgkmcnt(3)
	v_add_f32_e64 v70, v72, v88
	v_add_f32_e64 v71, v73, v89
	v_add_f32_e64 v72, v74, v90
	v_add_f32_e64 v73, v75, v91
	v_lshl_add_u32 v90, v124, 8, v190
	v_mfma_f32_32x32x16_bf16 v[0:15], v[132:135], v[128:131], v[0:15]
	s_waitcnt vmcnt(2) lgkmcnt(2)
	v_add_f32_e64 v74, v76, v92
	v_add_f32_e64 v75, v77, v93
	v_add_f32_e64 v76, v78, v94
	v_add_f32_e64 v77, v79, v95
	s_waitcnt vmcnt(1) lgkmcnt(1)
	v_pk_add_f32 v[78:79], v[80:81], v[96:97]
	v_pk_add_f32 v[80:81], v[82:83], v[98:99]
	s_waitcnt vmcnt(0) lgkmcnt(0)
	v_pk_add_f32 v[82:83], v[84:85], v[100:101]
	v_pk_add_f32 v[84:85], v[86:87], v[102:103]
	global_store_dwordx4 v[112:113], v[70:73], off
	global_store_dwordx4 v[114:115], v[74:77], off
	global_store_dwordx4 v[116:117], v[78:81], off
	global_store_dwordx4 v[118:119], v[82:85], off
	global_load_dwordx4 v[70:73], v[136:137], off
	v_lshl_add_u64 v[74:75], v[66:67], 0, v[106:107]
	v_lshl_add_u64 v[78:79], v[66:67], 0, v[108:109]
	v_lshl_add_u64 v[66:67], v[66:67], 0, v[110:111]
	global_load_dwordx4 v[74:77], v[74:75], off
	v_lshl_add_u32 v94, v126, 8, v190
	global_load_dwordx4 v[78:81], v[78:79], off
	v_lshl_add_u64 v[98:99], v[68:69], 0, v[104:105]
	global_load_dwordx4 v[82:85], v[66:67], off
	v_lshl_add_u32 v66, v120, 8, v190
	v_lshl_add_u32 v67, v122, 8, v190
	ds_read_b128 v[86:89], v66
	v_lshl_add_u64 v[100:101], v[68:69], 0, v[106:107]
	v_lshl_add_u64 v[102:103], v[68:69], 0, v[108:109]
	v_lshl_add_u64 v[104:105], v[68:69], 0, v[110:111]
	ds_read_b128 v[66:69], v67
	ds_read_b128 v[90:93], v90
	ds_read_b128 v[94:97], v94
	v_mov_b32_e32 v112, v158
	s_waitcnt vmcnt(3) lgkmcnt(3)
	v_pk_add_f32 v[70:71], v[70:71], v[86:87]
	v_pk_add_f32 v[72:73], v[72:73], v[88:89]
	s_waitcnt vmcnt(2) lgkmcnt(2)
	v_pk_add_f32 v[66:67], v[74:75], v[66:67]
	v_pk_add_f32 v[68:69], v[76:77], v[68:69]
	s_waitcnt vmcnt(1) lgkmcnt(1)
	v_pk_add_f32 v[74:75], v[78:79], v[90:91]
	v_pk_add_f32 v[76:77], v[80:81], v[92:93]
	s_waitcnt vmcnt(0) lgkmcnt(0)
	v_pk_add_f32 v[78:79], v[82:83], v[94:95]
	v_pk_add_f32 v[80:81], v[84:85], v[96:97]
	global_store_dwordx4 v[98:99], v[70:73], off
	global_store_dwordx4 v[100:101], v[66:69], off
	global_store_dwordx4 v[102:103], v[74:77], off
	global_store_dwordx4 v[104:105], v[78:81], off
	s_nop 0
	s_nop 0
	v_and_b32_e32 v66, 31, v112
	v_lshlrev_b32_e32 v67, 5, v112
	v_ashrrev_i32_e32 v68, 4, v112
	v_lshlrev_b32_e32 v69, 4, v112
	v_and_b32_e32 v67, 0xfffffc00, v67
	v_lshlrev_b32_e32 v66, 2, v66
	v_add_u32_e32 v70, 4, v68
	v_and_b32_e32 v144, 0xf0, v69
	v_ashrrev_i32_e32 v69, 31, v68
	v_add_u32_e32 v72, 8, v68
	v_add3_u32 v78, v172, v67, v66
	v_ashrrev_i32_e32 v71, 31, v70
	v_add_u32_e32 v74, 12, v68
	v_lshl_add_u64 v[66:67], v[156:157], 0, v[144:145]
	v_lshlrev_b64 v[76:77], 12, v[68:69]
	v_ashrrev_i32_e32 v73, 31, v72
	ds_write2_b32 v78, v48, v32 offset1:32
	ds_write2_b32 v78, v49, v33 offset0:64 offset1:96
	ds_write2_b32 v78, v50, v34 offset0:128 offset1:160
	ds_write2_b32 v78, v51, v35 offset0:192 offset1:224
	v_add_u32_e32 v69, 0x800, v78
	v_lshlrev_b64 v[34:35], 12, v[70:71]
	v_ashrrev_i32_e32 v75, 31, v74
	v_add_u32_e32 v79, 0x1000, v78
	v_add_u32_e32 v80, 0x1800, v78
	v_add_u32_e32 v81, 0x2000, v78
	v_add_u32_e32 v82, 0x2800, v78
	v_add_u32_e32 v83, 0x3000, v78
	v_add_u32_e32 v78, 0x3800, v78
	v_lshl_add_u64 v[32:33], v[66:67], 0, v[76:77]
	v_lshlrev_b64 v[48:49], 12, v[72:73]
	ds_write2_b32 v69, v52, v36 offset1:32
	ds_write2_b32 v69, v53, v37 offset0:64 offset1:96
	ds_write2_b32 v69, v54, v38 offset0:128 offset1:160
	ds_write2_b32 v69, v55, v39 offset0:192 offset1:224
	ds_write2_b32 v79, v56, v40 offset1:32
	ds_write2_b32 v79, v57, v41 offset0:64 offset1:96
	ds_write2_b32 v79, v58, v42 offset0:128 offset1:160
	ds_write2_b32 v79, v59, v43 offset0:192 offset1:224
	ds_write2_b32 v80, v60, v44 offset1:32
	ds_write2_b32 v80, v61, v45 offset0:64 offset1:96
	ds_write2_b32 v80, v62, v46 offset0:128 offset1:160
	ds_write2_b32 v80, v63, v47 offset0:192 offset1:224
	ds_write2_b32 v81, v16, v0 offset1:32
	ds_write2_b32 v81, v17, v1 offset0:64 offset1:96
	ds_write2_b32 v81, v18, v2 offset0:128 offset1:160
	ds_write2_b32 v81, v19, v3 offset0:192 offset1:224
	ds_write2_b32 v82, v20, v4 offset1:32
	ds_write2_b32 v82, v21, v5 offset0:64 offset1:96
	ds_write2_b32 v82, v22, v6 offset0:128 offset1:160
	ds_write2_b32 v82, v23, v7 offset0:192 offset1:224
	ds_write2_b32 v83, v24, v8 offset1:32
	ds_write2_b32 v83, v25, v9 offset0:64 offset1:96
	ds_write2_b32 v83, v26, v10 offset0:128 offset1:160
	ds_write2_b32 v83, v27, v11 offset0:192 offset1:224
	ds_write2_b32 v78, v28, v12 offset1:32
	ds_write2_b32 v78, v29, v13 offset0:64 offset1:96
	ds_write2_b32 v78, v30, v14 offset0:128 offset1:160
	ds_write2_b32 v78, v31, v15 offset0:192 offset1:224
	v_lshl_add_u64 v[0:1], v[66:67], 0, v[34:35]
	v_lshlrev_b64 v[50:51], 12, v[74:75]
	global_load_dwordx4 v[2:5], v[32:33], off offset:256
	global_load_dwordx4 v[6:9], v[0:1], off offset:256
	v_lshl_add_u64 v[0:1], v[66:67], 0, v[48:49]
	global_load_dwordx4 v[10:13], v[0:1], off offset:256
	v_lshl_add_u64 v[0:1], v[66:67], 0, v[50:51]
	global_load_dwordx4 v[14:17], v[0:1], off offset:256
	v_add_u32_e32 v60, v172, v144
	v_lshl_add_u32 v18, v68, 8, v60
	v_lshl_add_u32 v22, v70, 8, v60
	v_lshl_add_u32 v26, v72, 8, v60
	v_lshl_add_u32 v30, v74, 8, v60
	ds_read_b128 v[18:21], v18
	ds_read_b128 v[22:25], v22
	ds_read_b128 v[26:29], v26
	ds_read_b128 v[30:33], v30
	v_add_u32_e32 v36, 16, v68
	v_add_u32_e32 v38, 20, v68
	v_add_u32_e32 v40, 24, v68
	v_add_u32_e32 v42, 28, v68
	v_lshl_add_u64 v[0:1], v[64:65], 0, v[144:145]
	v_ashrrev_i32_e32 v37, 31, v36
	v_ashrrev_i32_e32 v39, 31, v38
	v_ashrrev_i32_e32 v41, 31, v40
	v_ashrrev_i32_e32 v43, 31, v42
	v_lshl_add_u64 v[44:45], v[0:1], 0, v[76:77]
	v_lshlrev_b64 v[46:47], 12, v[36:37]
	v_lshlrev_b64 v[52:53], 12, v[38:39]
	v_lshlrev_b64 v[54:55], 12, v[40:41]
	v_lshlrev_b64 v[56:57], 12, v[42:43]
	v_lshl_add_u64 v[34:35], v[0:1], 0, v[34:35]
	v_lshl_add_u64 v[48:49], v[0:1], 0, v[48:49]
	v_lshl_add_u64 v[50:51], v[0:1], 0, v[50:51]
	v_lshl_add_u64 v[58:59], v[66:67], 0, v[46:47]
	v_lshl_add_u64 v[46:47], v[0:1], 0, v[46:47]
	s_waitcnt vmcnt(3) lgkmcnt(3)
	v_pk_add_f32 v[2:3], v[2:3], v[18:19]
	v_pk_add_f32 v[4:5], v[4:5], v[20:21]
	s_waitcnt vmcnt(2) lgkmcnt(2)
	v_pk_add_f32 v[6:7], v[6:7], v[22:23]
	v_pk_add_f32 v[8:9], v[8:9], v[24:25]
	s_waitcnt vmcnt(1) lgkmcnt(1)
	v_pk_add_f32 v[10:11], v[10:11], v[26:27]
	v_pk_add_f32 v[12:13], v[12:13], v[28:29]
	s_waitcnt vmcnt(0) lgkmcnt(0)
	v_pk_add_f32 v[14:15], v[14:15], v[30:31]
	v_pk_add_f32 v[16:17], v[16:17], v[32:33]
	global_store_dwordx4 v[44:45], v[2:5], off offset:256
	global_store_dwordx4 v[34:35], v[6:9], off offset:256
	global_store_dwordx4 v[48:49], v[10:13], off offset:256
	global_store_dwordx4 v[50:51], v[14:17], off offset:256
	global_load_dwordx4 v[2:5], v[58:59], off offset:256
	v_lshl_add_u64 v[6:7], v[66:67], 0, v[52:53]
	v_lshl_add_u64 v[10:11], v[66:67], 0, v[54:55]
	v_lshl_add_u64 v[14:15], v[66:67], 0, v[56:57]
	global_load_dwordx4 v[6:9], v[6:7], off offset:256
	v_lshl_add_u32 v18, v36, 8, v60
	global_load_dwordx4 v[10:13], v[10:11], off offset:256
	v_lshl_add_u32 v22, v38, 8, v60
	global_load_dwordx4 v[14:17], v[14:15], off offset:256
	v_lshl_add_u32 v26, v40, 8, v60
	v_lshl_add_u32 v30, v42, 8, v60
	ds_read_b128 v[18:21], v18
	ds_read_b128 v[22:25], v22
	ds_read_b128 v[26:29], v26
	ds_read_b128 v[30:33], v30
	v_add_u32_e32 v34, 32, v68
	v_add_u32_e32 v44, 36, v68
	v_add_u32_e32 v48, 40, v68
	v_add_u32_e32 v50, 44, v68
	v_ashrrev_i32_e32 v35, 31, v34
	v_ashrrev_i32_e32 v45, 31, v44
	v_ashrrev_i32_e32 v49, 31, v48
	v_ashrrev_i32_e32 v51, 31, v50
	v_lshlrev_b64 v[36:37], 12, v[34:35]
	v_lshlrev_b64 v[38:39], 12, v[44:45]
	v_lshlrev_b64 v[40:41], 12, v[48:49]
	v_lshlrev_b64 v[42:43], 12, v[50:51]
	v_lshl_add_u64 v[52:53], v[0:1], 0, v[52:53]
	v_lshl_add_u64 v[54:55], v[0:1], 0, v[54:55]
	v_lshl_add_u64 v[56:57], v[0:1], 0, v[56:57]
	v_lshl_add_u64 v[58:59], v[66:67], 0, v[36:37]
	v_lshl_add_u64 v[36:37], v[0:1], 0, v[36:37]
	s_waitcnt vmcnt(3) lgkmcnt(3)
	v_pk_add_f32 v[2:3], v[2:3], v[18:19]
	v_pk_add_f32 v[4:5], v[4:5], v[20:21]
	v_lshl_add_u32 v18, v34, 8, v60
	s_waitcnt vmcnt(2) lgkmcnt(2)
	v_pk_add_f32 v[6:7], v[6:7], v[22:23]
	v_pk_add_f32 v[8:9], v[8:9], v[24:25]
	s_waitcnt vmcnt(1) lgkmcnt(1)
	v_pk_add_f32 v[10:11], v[10:11], v[26:27]
	v_pk_add_f32 v[12:13], v[12:13], v[28:29]
	s_waitcnt vmcnt(0) lgkmcnt(0)
	v_pk_add_f32 v[14:15], v[14:15], v[30:31]
	v_pk_add_f32 v[16:17], v[16:17], v[32:33]
	global_store_dwordx4 v[46:47], v[2:5], off offset:256
	global_store_dwordx4 v[52:53], v[6:9], off offset:256
	global_store_dwordx4 v[54:55], v[10:13], off offset:256
	global_store_dwordx4 v[56:57], v[14:17], off offset:256
	global_load_dwordx4 v[2:5], v[58:59], off offset:256
	v_lshl_add_u64 v[6:7], v[66:67], 0, v[38:39]
	v_lshl_add_u64 v[10:11], v[66:67], 0, v[40:41]
	v_lshl_add_u64 v[14:15], v[66:67], 0, v[42:43]
	global_load_dwordx4 v[6:9], v[6:7], off offset:256
	v_lshl_add_u32 v22, v44, 8, v60
	global_load_dwordx4 v[10:13], v[10:11], off offset:256
	v_lshl_add_u32 v26, v48, 8, v60
	global_load_dwordx4 v[14:17], v[14:15], off offset:256
	v_lshl_add_u32 v30, v50, 8, v60
	ds_read_b128 v[18:21], v18
	ds_read_b128 v[22:25], v22
	ds_read_b128 v[26:29], v26
	ds_read_b128 v[30:33], v30
	v_add_u32_e32 v46, 48, v68
	v_add_u32_e32 v52, 52, v68
	v_add_u32_e32 v54, 56, v68
	v_add_u32_e32 v56, 60, v68
	v_ashrrev_i32_e32 v47, 31, v46
	v_ashrrev_i32_e32 v53, 31, v52
	v_ashrrev_i32_e32 v55, 31, v54
	v_ashrrev_i32_e32 v57, 31, v56
	v_lshlrev_b64 v[34:35], 12, v[46:47]
	v_lshlrev_b64 v[44:45], 12, v[52:53]
	v_lshlrev_b64 v[48:49], 12, v[54:55]
	v_lshlrev_b64 v[50:51], 12, v[56:57]
	v_lshl_add_u64 v[38:39], v[0:1], 0, v[38:39]
	v_lshl_add_u64 v[40:41], v[0:1], 0, v[40:41]
	v_lshl_add_u64 v[42:43], v[0:1], 0, v[42:43]
	v_lshl_add_u64 v[58:59], v[66:67], 0, v[34:35]
	v_lshl_add_u64 v[34:35], v[0:1], 0, v[34:35]
	s_waitcnt vmcnt(3) lgkmcnt(3)
	v_pk_add_f32 v[2:3], v[2:3], v[18:19]
	v_pk_add_f32 v[4:5], v[4:5], v[20:21]
	v_lshl_add_u32 v18, v46, 8, v60
	s_waitcnt vmcnt(2) lgkmcnt(2)
	v_pk_add_f32 v[6:7], v[6:7], v[22:23]
	v_pk_add_f32 v[8:9], v[8:9], v[24:25]
	s_waitcnt vmcnt(1) lgkmcnt(1)
	v_pk_add_f32 v[10:11], v[10:11], v[26:27]
	v_pk_add_f32 v[12:13], v[12:13], v[28:29]
	s_waitcnt vmcnt(0) lgkmcnt(0)
	v_pk_add_f32 v[14:15], v[14:15], v[30:31]
	v_pk_add_f32 v[16:17], v[16:17], v[32:33]
	global_store_dwordx4 v[36:37], v[2:5], off offset:256
	global_store_dwordx4 v[38:39], v[6:9], off offset:256
	global_store_dwordx4 v[40:41], v[10:13], off offset:256
	global_store_dwordx4 v[42:43], v[14:17], off offset:256
	global_load_dwordx4 v[2:5], v[58:59], off offset:256
	v_lshl_add_u64 v[6:7], v[66:67], 0, v[44:45]
	v_lshl_add_u64 v[10:11], v[66:67], 0, v[48:49]
	v_lshl_add_u64 v[14:15], v[66:67], 0, v[50:51]
	global_load_dwordx4 v[6:9], v[6:7], off offset:256
	v_lshl_add_u32 v22, v52, 8, v60
	global_load_dwordx4 v[10:13], v[10:11], off offset:256
	v_lshl_add_u32 v26, v54, 8, v60
	global_load_dwordx4 v[14:17], v[14:15], off offset:256
	v_lshl_add_u32 v30, v56, 8, v60
	ds_read_b128 v[18:21], v18
	ds_read_b128 v[22:25], v22
	ds_read_b128 v[26:29], v26
	ds_read_b128 v[30:33], v30
	v_lshl_add_u64 v[36:37], v[0:1], 0, v[44:45]
	v_lshl_add_u64 v[38:39], v[0:1], 0, v[48:49]
	v_lshl_add_u64 v[40:41], v[0:1], 0, v[50:51]
	s_waitcnt vmcnt(3) lgkmcnt(3)
	v_pk_add_f32 v[0:1], v[2:3], v[18:19]
	v_pk_add_f32 v[2:3], v[4:5], v[20:21]
	s_waitcnt vmcnt(2) lgkmcnt(2)
	v_pk_add_f32 v[4:5], v[6:7], v[22:23]
	v_pk_add_f32 v[6:7], v[8:9], v[24:25]
	s_waitcnt vmcnt(1) lgkmcnt(1)
	v_pk_add_f32 v[8:9], v[10:11], v[26:27]
	v_pk_add_f32 v[10:11], v[12:13], v[28:29]
	s_waitcnt vmcnt(0) lgkmcnt(0)
	v_pk_add_f32 v[12:13], v[14:15], v[30:31]
	v_pk_add_f32 v[14:15], v[16:17], v[32:33]
	global_store_dwordx4 v[34:35], v[0:3], off offset:256
	global_store_dwordx4 v[36:37], v[4:7], off offset:256
	global_store_dwordx4 v[38:39], v[8:11], off offset:256
	global_store_dwordx4 v[40:41], v[12:15], off offset:256
	s_cbranch_scc0 .LBB0_674

.LBB0_788:
	s_ashr_i32 s0, s21, 31
	s_lshr_b32 s0, s0, 28
	s_add_i32 s0, s21, s0
	s_ashr_i32 s1, s0, 4
	s_add_i32 s11, s1, s56
	s_lshl_b32 s11, s11, 8
	v_add_u32_e32 v4, s11, v163
	v_ashrrev_i32_e32 v5, 31, v4
	s_and_b32 s0, s0, -16
	v_lshlrev_b64 v[4:5], 11, v[4:5]
	s_sub_i32 s10, s21, s0
	v_lshl_add_u64 v[6:7], s[28:29], 0, v[4:5]
	v_readfirstlane_b32 s0, v165
	v_lshl_add_u64 v[6:7], v[6:7], 0, v[138:139]
	s_mov_b32 m0, s0
	s_barrier
	global_load_lds_dwordx4 v[6:7], off
	v_add_u32_e32 v6, s11, v164
	s_lshl_b32 s22, s10, 8
	v_ashrrev_i32_e32 v7, 31, v6
	v_add_u32_e32 v0, s22, v163
	v_lshlrev_b64 v[6:7], 11, v[6:7]
	v_ashrrev_i32_e32 v1, 31, v0
	v_add_u32_e32 v2, s22, v164
	v_lshl_add_u64 v[8:9], s[28:29], 0, v[6:7]
	v_readfirstlane_b32 s0, v183
	v_lshlrev_b64 v[0:1], 11, v[0:1]
	v_ashrrev_i32_e32 v3, 31, v2
	v_lshl_add_u64 v[8:9], v[8:9], 0, v[138:139]
	s_mov_b32 m0, s0
	v_readfirstlane_b32 s0, v184
	v_lshl_add_u64 v[0:1], v[130:131], 0, v[0:1]
	v_lshlrev_b64 v[2:3], 11, v[2:3]
	global_load_lds_dwordx4 v[8:9], off
	s_mov_b32 m0, s0
	v_readfirstlane_b32 s0, v185
	v_lshl_add_u64 v[2:3], v[130:131], 0, v[2:3]
	global_load_lds_dwordx4 v[0:1], off
	s_mov_b32 m0, s0
	v_lshl_add_u64 v[8:9], v[132:133], 0, v[4:5]
	v_readfirstlane_b32 s0, v186
	global_load_lds_dwordx4 v[2:3], off
	v_lshl_add_u64 v[10:11], v[8:9], 0, s[4:5]
	s_mov_b32 m0, s0
	v_readfirstlane_b32 s0, v187
	global_load_lds_dwordx4 v[10:11], off
	v_lshl_add_u64 v[10:11], v[132:133], 0, v[6:7]
	v_lshl_add_u64 v[12:13], v[10:11], 0, s[4:5]
	s_mov_b32 m0, s0
	v_readfirstlane_b32 s0, v188
	global_load_lds_dwordx4 v[12:13], off
	v_lshl_add_u64 v[12:13], v[0:1], 0, 64
	s_mov_b32 m0, s0
	v_readfirstlane_b32 s0, v189
	global_load_lds_dwordx4 v[12:13], off
	v_lshl_add_u64 v[12:13], v[2:3], 0, 64
	s_mov_b32 m0, s0
	v_readfirstlane_b32 s0, v190
	global_load_lds_dwordx4 v[12:13], off
	v_lshl_add_u64 v[8:9], v[8:9], 0, s[6:7]
	s_mov_b32 m0, s0
	v_readfirstlane_b32 s0, v192
	global_load_lds_dwordx4 v[8:9], off
	v_lshl_add_u64 v[8:9], v[10:11], 0, s[6:7]
	s_mov_b32 m0, s0
	v_readfirstlane_b32 s0, v194
	global_load_lds_dwordx4 v[8:9], off
	v_lshl_add_u64 v[0:1], v[0:1], 0, s[8:9]
	s_mov_b32 m0, s0
	v_readfirstlane_b32 s0, v196
	global_load_lds_dwordx4 v[0:1], off
	v_lshl_add_u64 v[0:1], v[2:3], 0, s[8:9]
	s_mov_b32 m0, s0
	s_lshl_b32 s0, s21, 8
	global_load_lds_dwordx4 v[0:1], off
	v_add_u32_e32 v0, s0, v163
	s_lshl_b32 s1, s1, 12
	v_subrev_u32_e32 v0, s1, v0
	v_ashrrev_i32_e32 v1, 31, v0
	v_lshlrev_b64 v[0:1], 11, v[0:1]
	v_lshl_add_u64 v[140:141], v[134:135], 0, v[0:1]
	v_add_u32_e32 v0, s0, v164
	v_subrev_u32_e32 v0, s1, v0
	v_ashrrev_i32_e32 v1, 31, v0
	v_lshlrev_b64 v[0:1], 11, v[0:1]
	v_lshl_add_u64 v[142:143], v[134:135], 0, v[0:1]
	v_lshl_add_u64 v[144:145], v[136:137], 0, v[4:5]
	v_lshl_add_u64 v[146:147], v[136:137], 0, v[6:7]
	s_mov_b64 s[0:1], 0
	s_mov_b32 s12, 0x18000
	v_mov_b32_e32 v0, 0
	v_mov_b32_e32 v1, v129
	v_mov_b32_e32 v2, v129
	v_mov_b32_e32 v3, v129
	v_mov_b32_e32 v4, v129
	v_mov_b32_e32 v5, v129
	v_mov_b32_e32 v6, v129
	v_mov_b32_e32 v7, v129
	v_mov_b32_e32 v8, v129
	v_mov_b32_e32 v9, v129
	v_mov_b32_e32 v10, v129
	v_mov_b32_e32 v11, v129
	v_mov_b32_e32 v12, v129
	v_mov_b32_e32 v13, v129
	v_mov_b32_e32 v14, v129
	v_mov_b32_e32 v15, v129
	v_mov_b32_e32 v16, 0
	v_mov_b32_e32 v17, v129
	v_mov_b32_e32 v18, v129
	v_mov_b32_e32 v19, v129
	v_mov_b32_e32 v20, v129
	v_mov_b32_e32 v21, v129
	v_mov_b32_e32 v22, v129
	v_mov_b32_e32 v23, v129
	v_mov_b32_e32 v24, v129
	v_mov_b32_e32 v25, v129
	v_mov_b32_e32 v26, v129
	v_mov_b32_e32 v27, v129
	v_mov_b32_e32 v28, v129
	v_mov_b32_e32 v29, v129
	v_mov_b32_e32 v30, v129
	v_mov_b32_e32 v31, v129
	v_mov_b32_e32 v64, 0
	v_mov_b32_e32 v65, v129
	v_mov_b32_e32 v66, v129
	v_mov_b32_e32 v67, v129
	v_mov_b32_e32 v68, v129
	v_mov_b32_e32 v69, v129
	v_mov_b32_e32 v70, v129
	v_mov_b32_e32 v71, v129
	v_mov_b32_e32 v72, v129
	v_mov_b32_e32 v73, v129
	v_mov_b32_e32 v74, v129
	v_mov_b32_e32 v75, v129
	v_mov_b32_e32 v76, v129
	v_mov_b32_e32 v77, v129
	v_mov_b32_e32 v78, v129
	v_mov_b32_e32 v79, v129
	v_mov_b32_e32 v80, 0
	v_mov_b32_e32 v81, v129
	v_mov_b32_e32 v82, v129
	v_mov_b32_e32 v83, v129
	v_mov_b32_e32 v84, v129
	v_mov_b32_e32 v85, v129
	v_mov_b32_e32 v86, v129
	v_mov_b32_e32 v87, v129
	v_mov_b32_e32 v88, v129
	v_mov_b32_e32 v89, v129
	v_mov_b32_e32 v90, v129
	v_mov_b32_e32 v91, v129
	v_mov_b32_e32 v92, v129
	v_mov_b32_e32 v93, v129
	v_mov_b32_e32 v94, v129
	v_mov_b32_e32 v95, v129
	v_mov_b32_e32 v32, 0
	v_mov_b32_e32 v33, v129
	v_mov_b32_e32 v34, v129
	v_mov_b32_e32 v35, v129
	v_mov_b32_e32 v36, v129
	v_mov_b32_e32 v37, v129
	v_mov_b32_e32 v38, v129
	v_mov_b32_e32 v39, v129
	v_mov_b32_e32 v40, v129
	v_mov_b32_e32 v41, v129
	v_mov_b32_e32 v42, v129
	v_mov_b32_e32 v43, v129
	v_mov_b32_e32 v44, v129
	v_mov_b32_e32 v45, v129
	v_mov_b32_e32 v46, v129
	v_mov_b32_e32 v47, v129
	v_mov_b32_e32 v48, 0
	v_mov_b32_e32 v49, v129
	v_mov_b32_e32 v50, v129
	v_mov_b32_e32 v51, v129
	v_mov_b32_e32 v52, v129
	v_mov_b32_e32 v53, v129
	v_mov_b32_e32 v54, v129
	v_mov_b32_e32 v55, v129
	v_mov_b32_e32 v56, v129
	v_mov_b32_e32 v57, v129
	v_mov_b32_e32 v58, v129
	v_mov_b32_e32 v59, v129
	v_mov_b32_e32 v60, v129
	v_mov_b32_e32 v61, v129
	v_mov_b32_e32 v62, v129
	v_mov_b32_e32 v63, v129
	v_mov_b32_e32 v96, 0
	v_mov_b32_e32 v97, v129
	v_mov_b32_e32 v98, v129
	v_mov_b32_e32 v99, v129
	v_mov_b32_e32 v100, v129
	v_mov_b32_e32 v101, v129
	v_mov_b32_e32 v102, v129
	v_mov_b32_e32 v103, v129
	v_mov_b32_e32 v104, v129
	v_mov_b32_e32 v105, v129
	v_mov_b32_e32 v106, v129
	v_mov_b32_e32 v107, v129
	v_mov_b32_e32 v108, v129
	v_mov_b32_e32 v109, v129
	v_mov_b32_e32 v110, v129
	v_mov_b32_e32 v111, v129
	v_mov_b32_e32 v112, 0
	v_mov_b32_e32 v113, v129
	v_mov_b32_e32 v114, v129
	v_mov_b32_e32 v115, v129
	v_mov_b32_e32 v116, v129
	v_mov_b32_e32 v117, v129
	v_mov_b32_e32 v118, v129
	v_mov_b32_e32 v119, v129
	v_readfirstlane_b32 s99, v165
	v_mov_b32_e32 v120, v129
	v_mov_b32_e32 v121, v129
	v_mov_b32_e32 v122, v129
	v_mov_b32_e32 v123, v129
	v_mov_b32_e32 v124, v129
	v_mov_b32_e32 v125, v129
	v_mov_b32_e32 v126, v129
	v_mov_b32_e32 v127, v129
.LBB0_789:
	s_add_i32 s13, s12, 0xfffe8000
	s_and_b32 s13, s13, 0x18000
	s_add_i32 s13, s13, 16
	v_add_u32_e32 v128, s13, v166
	v_add_u32_e32 v160, s13, v168
	v_add_u32_e32 v152, v128, v167
	v_add_u32_e32 v156, v160, v167
	v_add_u32_e32 v161, s13, v170
	v_add_u32_e32 v128, v128, v171
	s_and_b32 s98, s12, 0x18000
	s_add_i32 s98, s98, s99
	s_waitcnt vmcnt(8)
	s_waitcnt lgkmcnt(0)
	s_barrier
	ds_read_b128 v[148:151], v152
	ds_read_b128 v[152:155], v152 offset:2048
	v_add_u32_e32 v199, v161, v167
	ds_read_b128 v[156:159], v156 offset:16384
	ds_read_b128 v[200:203], v199 offset:18432
	ds_read_b128 v[208:211], v199 offset:20480
	ds_read_b128 v[212:215], v199 offset:22528
	ds_read_b128 v[216:219], v128
	ds_read_b128 v[220:223], v128 offset:2048
	v_add_u32_e32 v128, v160, v171
	v_add_u32_e32 v160, v161, v171
	ds_read_b128 v[224:227], v128 offset:16384
	ds_read_b128 v[228:231], v160 offset:18432
	ds_read_b128 v[232:235], v160 offset:20480
	ds_read_b128 v[236:239], v160 offset:22528
	v_lshl_add_u64 v[250:251], v[144:145], 0, s[0:1]
	s_mov_b32 m0, s98
	s_waitcnt lgkmcnt(9)
	v_mfma_f32_32x32x16_bf16 v[112:127], v[148:151], v[156:159], v[112:127]
	s_waitcnt lgkmcnt(8)
	v_mfma_f32_32x32x16_bf16 v[96:111], v[148:151], v[200:203], v[96:111]
	global_load_lds_dwordx4 v[250:251], off
	v_lshl_add_u64 v[250:251], v[146:147], 0, s[0:1]
	s_add_i32 m0, s98, 0x2000
	s_waitcnt lgkmcnt(7)
	v_mfma_f32_32x32x16_bf16 v[48:63], v[148:151], v[208:211], v[48:63]
	s_waitcnt lgkmcnt(6)
	v_mfma_f32_32x32x16_bf16 v[32:47], v[148:151], v[212:215], v[32:47]
	v_mfma_f32_32x32x16_bf16 v[80:95], v[152:155], v[156:159], v[80:95]
	v_mfma_f32_32x32x16_bf16 v[64:79], v[152:155], v[200:203], v[64:79]
	global_load_lds_dwordx4 v[250:251], off
	v_lshl_add_u64 v[250:251], v[140:141], 0, s[0:1]
	s_add_i32 m0, s98, 0x4000
	v_mfma_f32_32x32x16_bf16 v[16:31], v[152:155], v[208:211], v[16:31]
	v_mfma_f32_32x32x16_bf16 v[0:15], v[152:155], v[212:215], v[0:15]
	s_waitcnt lgkmcnt(3)
	v_mfma_f32_32x32x16_bf16 v[112:127], v[216:219], v[224:227], v[112:127]
	s_waitcnt lgkmcnt(2)
	v_mfma_f32_32x32x16_bf16 v[96:111], v[216:219], v[228:231], v[96:111]
	global_load_lds_dwordx4 v[250:251], off
	v_lshl_add_u64 v[250:251], v[142:143], 0, s[0:1]
	s_add_i32 m0, s98, 0x6000
	s_waitcnt lgkmcnt(1)
	v_mfma_f32_32x32x16_bf16 v[48:63], v[216:219], v[232:235], v[48:63]
	s_waitcnt lgkmcnt(0)
	v_mfma_f32_32x32x16_bf16 v[32:47], v[216:219], v[236:239], v[32:47]
	v_mfma_f32_32x32x16_bf16 v[80:95], v[220:223], v[224:227], v[80:95]
	v_mfma_f32_32x32x16_bf16 v[64:79], v[220:223], v[228:231], v[64:79]
	global_load_lds_dwordx4 v[250:251], off
	s_add_u32 s0, s0, 64
	s_addc_u32 s1, s1, 0
	s_add_i32 s12, s12, 0x8000
	s_cmpk_eq_i32 s0, 0x740
	v_mfma_f32_32x32x16_bf16 v[16:31], v[220:223], v[232:235], v[16:31]
	v_mfma_f32_32x32x16_bf16 v[0:15], v[220:223], v[236:239], v[0:15]
	s_cbranch_scc0 .LBB0_789
	s_waitcnt vmcnt(8)
	v_add_u32_e32 v128, v180, v167
	s_waitcnt lgkmcnt(0)
	s_barrier
	ds_read_b128 v[140:143], v128 offset:32768
	ds_read_b128 v[144:147], v128 offset:34816
	v_add_u32_e32 v128, v181, v167
	v_add_u32_e32 v160, v182, v167
	ds_read_b128 v[148:151], v128 offset:49152
	ds_read_b128 v[152:155], v160 offset:51200
	ds_read_b128 v[156:159], v160 offset:53248
	ds_read_b128 v[200:203], v160 offset:55296
	v_add_u32_e32 v128, v180, v171
	ds_read_b128 v[208:211], v128 offset:32768
	ds_read_b128 v[212:215], v128 offset:34816
	v_add_u32_e32 v128, v181, v171
	v_add_u32_e32 v160, v182, v171
	ds_read_b128 v[216:219], v128 offset:49152
	ds_read_b128 v[220:223], v160 offset:51200
	ds_read_b128 v[224:227], v160 offset:53248
	ds_read_b128 v[228:231], v160 offset:55296
	s_waitcnt lgkmcnt(0)
	v_mfma_f32_32x32x16_bf16 v[112:127], v[140:143], v[148:151], v[112:127]
	s_waitcnt vmcnt(4)
	v_add_u32_e32 v128, v177, v171
	s_waitcnt lgkmcnt(0)
	s_barrier
	v_add_u32_e32 v160, v178, v167
	v_mfma_f32_32x32x16_bf16 v[96:111], v[140:143], v[152:155], v[96:111]
	v_mfma_f32_32x32x16_bf16 v[48:63], v[140:143], v[156:159], v[48:63]
	v_mfma_f32_32x32x16_bf16 v[32:47], v[140:143], v[200:203], v[32:47]
	v_mfma_f32_32x32x16_bf16 v[80:95], v[144:147], v[148:151], v[80:95]
	v_mfma_f32_32x32x16_bf16 v[64:79], v[144:147], v[152:155], v[64:79]
	v_add_u32_e32 v152, v178, v171
	v_mfma_f32_32x32x16_bf16 v[16:31], v[144:147], v[156:159], v[16:31]
	v_mfma_f32_32x32x16_bf16 v[0:15], v[144:147], v[200:203], v[0:15]
	ds_read_b128 v[140:143], v128 offset:4096
	ds_read_b128 v[144:147], v128 offset:2048
	ds_read_b128 v[148:151], v128 offset:6144
	ds_read_b128 v[152:155], v152
	v_add_u32_e32 v128, v179, v171
	ds_read_b128 v[156:159], v128 offset:2048
	ds_read_b128 v[200:203], v128
	v_add_u32_e32 v128, v177, v167
	v_mfma_f32_32x32x16_bf16 v[112:127], v[208:211], v[216:219], v[112:127]
	v_mfma_f32_32x32x16_bf16 v[96:111], v[208:211], v[220:223], v[96:111]
	v_mfma_f32_32x32x16_bf16 v[48:63], v[208:211], v[224:227], v[48:63]
	v_mfma_f32_32x32x16_bf16 v[32:47], v[208:211], v[228:231], v[32:47]
	v_mfma_f32_32x32x16_bf16 v[80:95], v[212:215], v[216:219], v[80:95]
	ds_read_b128 v[208:211], v128 offset:4096
	ds_read_b128 v[216:219], v128 offset:2048
	v_mfma_f32_32x32x16_bf16 v[64:79], v[212:215], v[220:223], v[64:79]
	v_mfma_f32_32x32x16_bf16 v[16:31], v[212:215], v[224:227], v[16:31]
	ds_read_b128 v[220:223], v128 offset:6144
	ds_read_b128 v[224:227], v160
	v_add_u32_e32 v128, v179, v167
	ds_read_b128 v[232:235], v128 offset:2048
	ds_read_b128 v[236:239], v128
	v_mfma_f32_32x32x16_bf16 v[0:15], v[212:215], v[228:231], v[0:15]
	s_waitcnt lgkmcnt(0)
	v_mfma_f32_32x32x16_bf16 v[112:127], v[236:239], v[224:227], v[112:127]
	s_waitcnt vmcnt(0)
	v_add_u32_e32 v128, v172, v171
	s_waitcnt lgkmcnt(0)
	s_barrier
	v_add_u32_e32 v160, v173, v171
	v_mfma_f32_32x32x16_bf16 v[96:111], v[236:239], v[216:219], v[96:111]
	v_mfma_f32_32x32x16_bf16 v[48:63], v[236:239], v[208:211], v[48:63]
	v_mfma_f32_32x32x16_bf16 v[32:47], v[236:239], v[220:223], v[32:47]
	v_mfma_f32_32x32x16_bf16 v[80:95], v[232:235], v[224:227], v[80:95]
	v_mfma_f32_32x32x16_bf16 v[64:79], v[232:235], v[216:219], v[64:79]
	v_mfma_f32_32x32x16_bf16 v[16:31], v[232:235], v[208:211], v[16:31]
	v_mfma_f32_32x32x16_bf16 v[0:15], v[232:235], v[220:223], v[0:15]
	v_mfma_f32_32x32x16_bf16 v[112:127], v[200:203], v[152:155], v[112:127]
	v_mfma_f32_32x32x16_bf16 v[96:111], v[200:203], v[144:147], v[96:111]
	v_mfma_f32_32x32x16_bf16 v[48:63], v[200:203], v[140:143], v[48:63]
	v_mfma_f32_32x32x16_bf16 v[32:47], v[200:203], v[148:151], v[32:47]
	v_mfma_f32_32x32x16_bf16 v[80:95], v[156:159], v[152:155], v[80:95]
	ds_read_b128 v[152:155], v128 offset:4096
	ds_read_b128 v[200:203], v128 offset:2048
	v_mfma_f32_32x32x16_bf16 v[64:79], v[156:159], v[144:147], v[64:79]
	ds_read_b128 v[144:147], v128 offset:6144
	ds_read_b128 v[208:211], v160
	v_add_u32_e32 v128, v174, v171
	ds_read_b128 v[212:215], v128 offset:2048
	ds_read_b128 v[216:219], v128
	v_add_u32_e32 v128, v172, v167
	v_add_u32_e32 v160, v173, v167
	v_mfma_f32_32x32x16_bf16 v[16:31], v[156:159], v[140:143], v[16:31]
	ds_read_b128 v[140:143], v128 offset:4096
	ds_read_b128 v[220:223], v128 offset:2048
	ds_read_b128 v[224:227], v128 offset:6144
	ds_read_b128 v[228:231], v160
	v_add_u32_e32 v128, v174, v167
	ds_read_b128 v[232:235], v128 offset:2048
	ds_read_b128 v[236:239], v128
	v_mfma_f32_32x32x16_bf16 v[0:15], v[156:159], v[148:151], v[0:15]
	s_waitcnt lgkmcnt(0)
	v_mfma_f32_32x32x16_bf16 v[112:127], v[236:239], v[228:231], v[112:127]
	s_waitcnt lgkmcnt(0)
	s_ashr_i32 s23, s10, 2
	s_and_b32 s0, s22, 0x300
	v_mov_b32_e32 v148, v162
	v_or_b32_e32 v199, s0, v169
	s_mov_b64 s[12:13], -1
	s_mov_b64 s[0:1], 0
	v_mfma_f32_32x32x16_bf16 v[96:111], v[236:239], v[220:223], v[96:111]
	s_cmp_lt_i32 s23, 2
	s_barrier
	v_mfma_f32_32x32x16_bf16 v[48:63], v[236:239], v[140:143], v[48:63]
	v_mfma_f32_32x32x16_bf16 v[32:47], v[236:239], v[224:227], v[32:47]
	v_mfma_f32_32x32x16_bf16 v[80:95], v[232:235], v[228:231], v[80:95]
	v_mfma_f32_32x32x16_bf16 v[64:79], v[232:235], v[220:223], v[64:79]
	v_mfma_f32_32x32x16_bf16 v[16:31], v[232:235], v[140:143], v[16:31]
	v_add_u32_e32 v140, s11, v175
	s_mov_b64 s[10:11], 0
	v_mfma_f32_32x32x16_bf16 v[0:15], v[232:235], v[224:227], v[0:15]
	v_mfma_f32_32x32x16_bf16 v[112:127], v[216:219], v[208:211], v[112:127]
	v_mfma_f32_32x32x16_bf16 v[96:111], v[216:219], v[200:203], v[96:111]
	v_mfma_f32_32x32x16_bf16 v[48:63], v[216:219], v[152:155], v[48:63]
	v_mfma_f32_32x32x16_bf16 v[32:47], v[216:219], v[144:147], v[32:47]
	v_mfma_f32_32x32x16_bf16 v[80:95], v[212:215], v[208:211], v[80:95]
	v_mfma_f32_32x32x16_bf16 v[64:79], v[212:215], v[200:203], v[64:79]
	v_mfma_f32_32x32x16_bf16 v[16:31], v[212:215], v[152:155], v[16:31]
	v_mfma_f32_32x32x16_bf16 v[0:15], v[212:215], v[144:147], v[0:15]
	s_cbranch_scc0 .LBB0_799
	s_and_b64 vcc, exec, s[12:13]
	s_cbranch_vccnz .LBB0_802

	.amdhsa_kernel _Z4mega6Params
		.amdhsa_group_segment_fixed_size 16
		.amdhsa_private_segment_fixed_size 0
		.amdhsa_kernarg_size 392
		.amdhsa_user_sgpr_count 2
		.amdhsa_user_sgpr_dispatch_ptr 0
		.amdhsa_user_sgpr_queue_ptr 0
		.amdhsa_user_sgpr_kernarg_segment_ptr 1
		.amdhsa_user_sgpr_dispatch_id 0
		.amdhsa_user_sgpr_kernarg_preload_length 0
		.amdhsa_user_sgpr_kernarg_preload_offset 0
		.amdhsa_user_sgpr_private_segment_size 0
		.amdhsa_uses_dynamic_stack 0
		.amdhsa_enable_private_segment 0
		.amdhsa_system_sgpr_workgroup_id_x 1
		.amdhsa_system_sgpr_workgroup_id_y 0
		.amdhsa_system_sgpr_workgroup_id_z 0
		.amdhsa_system_sgpr_workgroup_info 0
		.amdhsa_system_vgpr_workitem_id 2
		.amdhsa_next_free_vgpr 252
		.amdhsa_next_free_sgpr 100
		.amdhsa_accum_offset 252
		.amdhsa_reserve_vcc 1
		.amdhsa_float_round_mode_32 0
		.amdhsa_float_round_mode_16_64 0
		.amdhsa_float_denorm_mode_32 3
		.amdhsa_float_denorm_mode_16_64 3
		.amdhsa_dx10_clamp 1
		.amdhsa_ieee_mode 1
		.amdhsa_fp16_overflow 0
		.amdhsa_tg_split 0
		.amdhsa_exception_fp_ieee_invalid_op 0
		.amdhsa_exception_fp_denorm_src 0
		.amdhsa_exception_fp_ieee_div_zero 0
		.amdhsa_exception_fp_ieee_overflow 0
		.amdhsa_exception_fp_ieee_underflow 0
		.amdhsa_exception_fp_ieee_inexact 0
		.amdhsa_exception_int_div_zero 0
	.end_amdhsa_kernel

amdhsa.kernels:
  - .agpr_count:     0
    .args:
      - .offset:         0
        .size:           136
        .value_kind:     by_value
      - .offset:         136
        .size:           4
        .value_kind:     hidden_block_count_x
      - .offset:         140
        .size:           4
        .value_kind:     hidden_block_count_y
      - .offset:         144
        .size:           4
        .value_kind:     hidden_block_count_z
      - .offset:         148
        .size:           2
        .value_kind:     hidden_group_size_x
      - .offset:         150
        .size:           2
        .value_kind:     hidden_group_size_y
      - .offset:         152
        .size:           2
        .value_kind:     hidden_group_size_z
      - .offset:         154
        .size:           2
        .value_kind:     hidden_remainder_x
      - .offset:         156
        .size:           2
        .value_kind:     hidden_remainder_y
      - .offset:         158
        .size:           2
        .value_kind:     hidden_remainder_z
      - .offset:         176
        .size:           8
        .value_kind:     hidden_global_offset_x
      - .offset:         184
        .size:           8
        .value_kind:     hidden_global_offset_y
      - .offset:         192
        .size:           8
        .value_kind:     hidden_global_offset_z
      - .offset:         200
        .size:           2
        .value_kind:     hidden_grid_dims
      - .offset:         224
        .size:           8
        .value_kind:     hidden_multigrid_sync_arg
      - .offset:         256
        .size:           4
        .value_kind:     hidden_dynamic_lds_size
    .group_segment_fixed_size: 16
    .kernarg_segment_align: 8
    .kernarg_segment_size: 392
    .language:       OpenCL C
    .language_version:
      - 2
      - 0
    .max_flat_workgroup_size: 512
    .name:           _Z4mega6Params
    .private_segment_fixed_size: 0
    .sgpr_count:     106
    .sgpr_spill_count: 6
    .symbol:         _Z4mega6Params.kd
    .uniform_work_group_size: 1
    .uses_dynamic_stack: false
    .vgpr_count:     252
    .vgpr_spill_count: 0
    .wavefront_size: 64
